# prep_mod rewritten: 28 weight-row loads in flight across both passes, silu(c) staging pipelined; wif staging loads batched
# speedup vs baseline: 1.0093x; 1.0093x over previous
; __device__ __forceinline__ int obx() { int b = blockIdx.x; asm volatile("" : "+s"(b)); return b; }
; __device__ __forceinline__ int ogx() { int g = gridDim.x; asm volatile("" : "+s"(g)); return g; }
; __device__ NOINL void prep_mod(const float* c, const float* wada, const float* bada, float* mod, LAS unsigned char* lds, int wv) {
;     ...
;     for (int u = obx(); u < 192; u += ogx()) {
;         const int l = u / 96, j0 = (u % 96) * 128;
;         float acc[16];
; #pragma unroll
;         for (int b = 0; b < 16; ++b) acc[b] = 0.f;
;         for (int pass = 0; pass < 2; ++pass) {
;             __syncthreads();
; #pragma unroll 4
;             for (int i = 0; i < 32; ++i) { const int idx = i * 512 + tid, b = idx >> 10, r = idx & 1023, kq2 = r >> 8, kk = r & 255;
;                 const float v = c[b * 2048 + kq2 * 512 + pass * 256 + kk]; cs[idx] = v / (1.0f + expf(-v)); }
;             __syncthreads();
;             const float* wp = wada + ((size_t)l * 2048 + kq * 512 + pass * 256) * 12288 + j0 + j;
; #pragma unroll 4
.LBB0_2:
	s_barrier
	s_mul_hi_i32 s2, s10, 0x2aaaaaab
	s_lshr_b32 s3, s2, 31
	s_ashr_i32 s2, s2, 4
	s_add_i32 s2, s2, s3
	s_mul_i32 s3, s2, 0x60
	s_sub_i32 s3, s10, s3
	s_lshl_b32 s6, s3, 7
	s_ashr_i32 s3, s2, 31
	s_ashr_i32 s7, s6, 31
	s_mul_i32 s24, s2, 0x6000000
	s_lshl_b32 s25, s6, 2
	s_add_u32 s24, s24, s25
	s_add_u32 s8, s56, s24
	s_addc_u32 s9, s57, 0
	s_mov_b32 s29, s56
	s_mov_b32 s30, s57
	s_mov_b32 s24, 0x1800000
	v_mul_lo_u32 v186, v46, s24
	v_lshl_add_u32 v186, v78, 2, v186
	v_and_b32_e32 v187, 0x200, v89
	v_or_b32_e32 v187, v187, v79
	v_lshlrev_b32_e32 v187, 2, v187
	v_mov_b32_e32 v93, v80
	s_mov_b32 s24, 0
	v_mov_b32_e32 v146, 0
	v_mov_b32_e32 v147, 0
	v_mov_b32_e32 v148, 0
	v_mov_b32_e32 v149, 0
	v_mov_b32_e32 v150, 0
	v_mov_b32_e32 v151, 0
	v_mov_b32_e32 v152, 0
	v_mov_b32_e32 v153, 0
	v_mov_b32_e32 v154, 0
	v_mov_b32_e32 v155, 0
	v_mov_b32_e32 v156, 0
	v_mov_b32_e32 v157, 0
	v_mov_b32_e32 v158, 0
	v_mov_b32_e32 v159, 0
	v_mov_b32_e32 v168, 0
	v_mov_b32_e32 v169, 0
	v_mov_b32_e32 v170, 0
	v_mov_b32_e32 v171, 0
	v_mov_b32_e32 v172, 0
	v_mov_b32_e32 v173, 0
	v_mov_b32_e32 v174, 0
	v_mov_b32_e32 v175, 0
	v_mov_b32_e32 v176, 0
	v_mov_b32_e32 v177, 0
	v_mov_b32_e32 v178, 0
	v_mov_b32_e32 v179, 0
	v_mov_b32_e32 v180, 0
	v_mov_b32_e32 v181, 0
	v_mov_b32_e32 v182, 0
	v_mov_b32_e32 v183, 0
	v_mov_b32_e32 v184, 0
	v_mov_b32_e32 v185, 0
	global_load_dword v94, v186, s[8:9]
	s_add_u32 s8, s8, 0xc000
	s_addc_u32 s9, s9, 0
	global_load_dword v95, v186, s[8:9]
	s_add_u32 s8, s8, 0xc000
	s_addc_u32 s9, s9, 0
	global_load_dword v96, v186, s[8:9]
	s_add_u32 s8, s8, 0xc000
	s_addc_u32 s9, s9, 0
	global_load_dword v97, v186, s[8:9]
	s_add_u32 s8, s8, 0xc000
	s_addc_u32 s9, s9, 0
	global_load_dword v98, v186, s[8:9]
	s_add_u32 s8, s8, 0xc000
	s_addc_u32 s9, s9, 0
	global_load_dword v99, v186, s[8:9]
	s_add_u32 s8, s8, 0xc000
	s_addc_u32 s9, s9, 0
	global_load_dword v100, v186, s[8:9]
	s_add_u32 s8, s8, 0xc000
	s_addc_u32 s9, s9, 0
	global_load_dword v101, v186, s[8:9]
	s_add_u32 s8, s8, 0xc000
	s_addc_u32 s9, s9, 0
	global_load_dword v102, v186, s[8:9]
	s_add_u32 s8, s8, 0xc000
	s_addc_u32 s9, s9, 0
	global_load_dword v103, v186, s[8:9]
	s_add_u32 s8, s8, 0xc000
	s_addc_u32 s9, s9, 0
	global_load_dword v104, v186, s[8:9]
	s_add_u32 s8, s8, 0xc000
	s_addc_u32 s9, s9, 0
	global_load_dword v105, v186, s[8:9]
	s_add_u32 s8, s8, 0xc000
	s_addc_u32 s9, s9, 0
	global_load_dword v106, v186, s[8:9]
	s_add_u32 s8, s8, 0xc000
	s_addc_u32 s9, s9, 0
	global_load_dword v107, v186, s[8:9]
	s_add_u32 s8, s8, 0xc000
	s_addc_u32 s9, s9, 0
	global_load_dword v108, v186, s[8:9]
	s_add_u32 s8, s8, 0xc000
	s_addc_u32 s9, s9, 0
	global_load_dword v109, v186, s[8:9]
	s_add_u32 s8, s8, 0xc000
	s_addc_u32 s9, s9, 0
	global_load_dword v110, v186, s[8:9]
	s_add_u32 s8, s8, 0xc000
	s_addc_u32 s9, s9, 0
	global_load_dword v111, v186, s[8:9]
	s_add_u32 s8, s8, 0xc000
	s_addc_u32 s9, s9, 0
	global_load_dword v112, v186, s[8:9]
	s_add_u32 s8, s8, 0xc000
	s_addc_u32 s9, s9, 0
	global_load_dword v113, v186, s[8:9]
	s_add_u32 s8, s8, 0xc000
	s_addc_u32 s9, s9, 0
	global_load_dword v114, v186, s[8:9]
	s_add_u32 s8, s8, 0xc000
	s_addc_u32 s9, s9, 0
	global_load_dword v115, v186, s[8:9]
	s_add_u32 s8, s8, 0xc000
	s_addc_u32 s9, s9, 0
	global_load_dword v116, v186, s[8:9]
	s_add_u32 s8, s8, 0xc000
	s_addc_u32 s9, s9, 0
	global_load_dword v117, v186, s[8:9]
	s_add_u32 s8, s8, 0xc000
	s_addc_u32 s9, s9, 0
	global_load_dword v118, v186, s[8:9]
	s_add_u32 s8, s8, 0xc000
	s_addc_u32 s9, s9, 0
	global_load_dword v119, v186, s[8:9]
	s_add_u32 s8, s8, 0xc000
	s_addc_u32 s9, s9, 0
	global_load_dword v120, v186, s[8:9]
	s_add_u32 s8, s8, 0xc000
	s_addc_u32 s9, s9, 0
	global_load_dword v121, v186, s[8:9]
	s_add_u32 s8, s8, 0xc000
	s_addc_u32 s9, s9, 0
	s_mov_b32 s26, s54
	s_mov_b32 s27, s55
	s_mov_b32 s28, 0
	v_mov_b32_e32 v188, v90
	global_load_dword v2, v187, s[26:27]
	s_add_u32 s26, s26, 0x1000
	s_addc_u32 s27, s27, 0
	global_load_dword v3, v187, s[26:27]
	s_add_u32 s26, s26, 0x1000
	s_addc_u32 s27, s27, 0
	global_load_dword v4, v187, s[26:27]
	s_add_u32 s26, s26, 0x1000
	s_addc_u32 s27, s27, 0
	global_load_dword v5, v187, s[26:27]
	s_add_u32 s26, s26, 0x1000
	s_addc_u32 s27, s27, 0
	global_load_dword v6, v187, s[26:27]
	s_add_u32 s26, s26, 0x1000
	s_addc_u32 s27, s27, 0
	global_load_dword v7, v187, s[26:27]
	s_add_u32 s26, s26, 0x1000
	s_addc_u32 s27, s27, 0
	global_load_dword v8, v187, s[26:27]
	s_add_u32 s26, s26, 0x1000
	s_addc_u32 s27, s27, 0
	global_load_dword v9, v187, s[26:27]
	s_add_u32 s26, s26, 0x1000
	s_addc_u32 s27, s27, 0
; __device__ NOINL void prep_mod(const float* c, const float* wada, const float* bada, float* mod, LAS unsigned char* lds, int wv) {
;     ...
;             for (int i = 0; i < 32; ++i) { const int idx = i * 512 + tid, b = idx >> 10, r = idx & 1023, kq2 = r >> 8, kk = r & 255;
;                 const float v = c[b * 2048 + kq2 * 512 + pass * 256 + kk]; cs[idx] = v / (1.0f + expf(-v)); }
.Lpm_silu0:
	s_waitcnt vmcnt(4)
	v_mul_f32_e32 v10, 0xbfb8aa3b, v2
	v_fma_f32 v11, v2, s12, -v10
	v_rndne_f32_e32 v12, v10
	v_fmac_f32_e32 v11, 0xb2a5705f, v2
	v_sub_f32_e32 v10, v10, v12
	v_add_f32_e32 v10, v10, v11
	v_cvt_i32_f32_e32 v12, v12
	v_exp_f32_e32 v10, v10
	v_cmp_nlt_f32_e32 vcc, s13, v2
	v_ldexp_f32 v10, v10, v12
	s_nop 0
	v_cndmask_b32_e32 v10, 0, v10, vcc
	v_cmp_ngt_f32_e32 vcc, s14, v2
	s_nop 1
	v_cndmask_b32_e32 v10, v91, v10, vcc
	v_add_f32_e32 v10, 1.0, v10
	v_div_scale_f32 v11, s[22:23], v10, v10, v2
	v_rcp_f32_e32 v13, v11
	v_div_scale_f32 v12, vcc, v2, v10, v2
	v_fma_f32 v14, -v11, v13, 1.0
	v_fmac_f32_e32 v13, v14, v13
	v_mul_f32_e32 v14, v12, v13
	v_fma_f32 v15, -v11, v14, v12
	v_fmac_f32_e32 v14, v15, v13
	v_fma_f32 v11, -v11, v14, v12
	v_div_fmas_f32 v11, v11, v13, v14
	v_div_fixup_f32 v2, v11, v10, v2
	ds_write_b32 v188, v2
	v_mul_f32_e32 v10, 0xbfb8aa3b, v3
	v_fma_f32 v11, v3, s12, -v10
	v_rndne_f32_e32 v12, v10
	v_fmac_f32_e32 v11, 0xb2a5705f, v3
	v_sub_f32_e32 v10, v10, v12
	v_add_f32_e32 v10, v10, v11
	v_cvt_i32_f32_e32 v12, v12
	v_exp_f32_e32 v10, v10
	v_cmp_nlt_f32_e32 vcc, s13, v3
	v_ldexp_f32 v10, v10, v12
	s_nop 0
	v_cndmask_b32_e32 v10, 0, v10, vcc
	v_cmp_ngt_f32_e32 vcc, s14, v3
	s_nop 1
	v_cndmask_b32_e32 v10, v91, v10, vcc
	v_add_f32_e32 v10, 1.0, v10
	v_div_scale_f32 v11, s[22:23], v10, v10, v3
	v_rcp_f32_e32 v13, v11
	v_div_scale_f32 v12, vcc, v3, v10, v3
	v_fma_f32 v14, -v11, v13, 1.0
	v_fmac_f32_e32 v13, v14, v13
	v_mul_f32_e32 v14, v12, v13
	v_fma_f32 v15, -v11, v14, v12
	v_fmac_f32_e32 v14, v15, v13
	v_fma_f32 v11, -v11, v14, v12
	v_div_fmas_f32 v11, v11, v13, v14
	v_div_fixup_f32 v3, v11, v10, v3
	ds_write_b32 v188, v3 offset:2048
	v_mul_f32_e32 v10, 0xbfb8aa3b, v4
	v_fma_f32 v11, v4, s12, -v10
	v_rndne_f32_e32 v12, v10
	v_fmac_f32_e32 v11, 0xb2a5705f, v4
	v_sub_f32_e32 v10, v10, v12
	v_add_f32_e32 v10, v10, v11
	v_cvt_i32_f32_e32 v12, v12
	v_exp_f32_e32 v10, v10
	v_cmp_nlt_f32_e32 vcc, s13, v4
	v_ldexp_f32 v10, v10, v12
	s_nop 0
	v_cndmask_b32_e32 v10, 0, v10, vcc
	v_cmp_ngt_f32_e32 vcc, s14, v4
	s_nop 1
	v_cndmask_b32_e32 v10, v91, v10, vcc
	v_add_f32_e32 v10, 1.0, v10
	v_div_scale_f32 v11, s[22:23], v10, v10, v4
	v_rcp_f32_e32 v13, v11
	v_div_scale_f32 v12, vcc, v4, v10, v4
	v_fma_f32 v14, -v11, v13, 1.0
	v_fmac_f32_e32 v13, v14, v13
	v_mul_f32_e32 v14, v12, v13
	v_fma_f32 v15, -v11, v14, v12
	v_fmac_f32_e32 v14, v15, v13
	v_fma_f32 v11, -v11, v14, v12
	v_div_fmas_f32 v11, v11, v13, v14
	v_div_fixup_f32 v4, v11, v10, v4
	ds_write_b32 v188, v4 offset:4096
	v_mul_f32_e32 v10, 0xbfb8aa3b, v5
	v_fma_f32 v11, v5, s12, -v10
	v_rndne_f32_e32 v12, v10
	v_fmac_f32_e32 v11, 0xb2a5705f, v5
	v_sub_f32_e32 v10, v10, v12
	v_add_f32_e32 v10, v10, v11
	v_cvt_i32_f32_e32 v12, v12
	v_exp_f32_e32 v10, v10
	v_cmp_nlt_f32_e32 vcc, s13, v5
	v_ldexp_f32 v10, v10, v12
	s_nop 0
	v_cndmask_b32_e32 v10, 0, v10, vcc
	v_cmp_ngt_f32_e32 vcc, s14, v5
	s_nop 1
	v_cndmask_b32_e32 v10, v91, v10, vcc
	v_add_f32_e32 v10, 1.0, v10
	v_div_scale_f32 v11, s[22:23], v10, v10, v5
	v_rcp_f32_e32 v13, v11
	v_div_scale_f32 v12, vcc, v5, v10, v5
	v_fma_f32 v14, -v11, v13, 1.0
	v_fmac_f32_e32 v13, v14, v13
	v_mul_f32_e32 v14, v12, v13
	v_fma_f32 v15, -v11, v14, v12
	v_fmac_f32_e32 v14, v15, v13
	v_fma_f32 v11, -v11, v14, v12
	v_div_fmas_f32 v11, v11, v13, v14
	v_div_fixup_f32 v5, v11, v10, v5
	ds_write_b32 v188, v5 offset:6144
	s_cmp_eq_u32 s28, 3
	s_cselect_b32 s26, s54, s26
	s_cselect_b32 s27, s55, s27
	global_load_dword v2, v187, s[26:27]
	s_add_u32 s26, s26, 0x1000
	s_addc_u32 s27, s27, 0
	global_load_dword v3, v187, s[26:27]
	s_add_u32 s26, s26, 0x1000
	s_addc_u32 s27, s27, 0
	global_load_dword v4, v187, s[26:27]
	s_add_u32 s26, s26, 0x1000
	s_addc_u32 s27, s27, 0
	global_load_dword v5, v187, s[26:27]
	s_add_u32 s26, s26, 0x1000
	s_addc_u32 s27, s27, 0
	s_waitcnt vmcnt(4)
	v_mul_f32_e32 v10, 0xbfb8aa3b, v6
	v_fma_f32 v11, v6, s12, -v10
	v_rndne_f32_e32 v12, v10
	v_fmac_f32_e32 v11, 0xb2a5705f, v6
	v_sub_f32_e32 v10, v10, v12
	v_add_f32_e32 v10, v10, v11
	v_cvt_i32_f32_e32 v12, v12
	v_exp_f32_e32 v10, v10
	v_cmp_nlt_f32_e32 vcc, s13, v6
	v_ldexp_f32 v10, v10, v12
	s_nop 0
	v_cndmask_b32_e32 v10, 0, v10, vcc
	v_cmp_ngt_f32_e32 vcc, s14, v6
	s_nop 1
	v_cndmask_b32_e32 v10, v91, v10, vcc
	v_add_f32_e32 v10, 1.0, v10
	v_div_scale_f32 v11, s[22:23], v10, v10, v6
	v_rcp_f32_e32 v13, v11
	v_div_scale_f32 v12, vcc, v6, v10, v6
	v_fma_f32 v14, -v11, v13, 1.0
	v_fmac_f32_e32 v13, v14, v13
	v_mul_f32_e32 v14, v12, v13
	v_fma_f32 v15, -v11, v14, v12
	v_fmac_f32_e32 v14, v15, v13
	v_fma_f32 v11, -v11, v14, v12
	v_div_fmas_f32 v11, v11, v13, v14
	v_div_fixup_f32 v6, v11, v10, v6
	ds_write_b32 v188, v6 offset:8192
	v_mul_f32_e32 v10, 0xbfb8aa3b, v7
	v_fma_f32 v11, v7, s12, -v10
	v_rndne_f32_e32 v12, v10
	v_fmac_f32_e32 v11, 0xb2a5705f, v7
	v_sub_f32_e32 v10, v10, v12
	v_add_f32_e32 v10, v10, v11
	v_cvt_i32_f32_e32 v12, v12
	v_exp_f32_e32 v10, v10
	v_cmp_nlt_f32_e32 vcc, s13, v7
	v_ldexp_f32 v10, v10, v12
	s_nop 0
	v_cndmask_b32_e32 v10, 0, v10, vcc
	v_cmp_ngt_f32_e32 vcc, s14, v7
	s_nop 1
	v_cndmask_b32_e32 v10, v91, v10, vcc
	v_add_f32_e32 v10, 1.0, v10
	v_div_scale_f32 v11, s[22:23], v10, v10, v7
	v_rcp_f32_e32 v13, v11
	v_div_scale_f32 v12, vcc, v7, v10, v7
	v_fma_f32 v14, -v11, v13, 1.0
	v_fmac_f32_e32 v13, v14, v13
	v_mul_f32_e32 v14, v12, v13
	v_fma_f32 v15, -v11, v14, v12
	v_fmac_f32_e32 v14, v15, v13
	v_fma_f32 v11, -v11, v14, v12
	v_div_fmas_f32 v11, v11, v13, v14
	v_div_fixup_f32 v7, v11, v10, v7
	ds_write_b32 v188, v7 offset:10240
	v_mul_f32_e32 v10, 0xbfb8aa3b, v8
	v_fma_f32 v11, v8, s12, -v10
	v_rndne_f32_e32 v12, v10
; __device__ NOINL void prep_mod(const float* c, const float* wada, const float* bada, float* mod, LAS unsigned char* lds, int wv) {
;     ...
;         for (int pass = 0; pass < 2; ++pass) {
;             __syncthreads();
; #pragma unroll 4
;             for (int i = 0; i < 32; ++i) { const int idx = i * 512 + tid, b = idx >> 10, r = idx & 1023, kq2 = r >> 8, kk = r & 255;
;                 const float v = c[b * 2048 + kq2 * 512 + pass * 256 + kk]; cs[idx] = v / (1.0f + expf(-v)); }
;             __syncthreads();
	v_fmac_f32_e32 v11, 0xb2a5705f, v8
	v_sub_f32_e32 v10, v10, v12
	v_add_f32_e32 v10, v10, v11
	v_cvt_i32_f32_e32 v12, v12
	v_exp_f32_e32 v10, v10
	v_cmp_nlt_f32_e32 vcc, s13, v8
	v_ldexp_f32 v10, v10, v12
	s_nop 0
	v_cndmask_b32_e32 v10, 0, v10, vcc
	v_cmp_ngt_f32_e32 vcc, s14, v8
	s_nop 1
	v_cndmask_b32_e32 v10, v91, v10, vcc
	v_add_f32_e32 v10, 1.0, v10
	v_div_scale_f32 v11, s[22:23], v10, v10, v8
	v_rcp_f32_e32 v13, v11
	v_div_scale_f32 v12, vcc, v8, v10, v8
	v_fma_f32 v14, -v11, v13, 1.0
	v_fmac_f32_e32 v13, v14, v13
	v_mul_f32_e32 v14, v12, v13
	v_fma_f32 v15, -v11, v14, v12
	v_fmac_f32_e32 v14, v15, v13
	v_fma_f32 v11, -v11, v14, v12
	v_div_fmas_f32 v11, v11, v13, v14
	v_div_fixup_f32 v8, v11, v10, v8
	ds_write_b32 v188, v8 offset:12288
	v_mul_f32_e32 v10, 0xbfb8aa3b, v9
	v_fma_f32 v11, v9, s12, -v10
	v_rndne_f32_e32 v12, v10
	v_fmac_f32_e32 v11, 0xb2a5705f, v9
	v_sub_f32_e32 v10, v10, v12
	v_add_f32_e32 v10, v10, v11
	v_cvt_i32_f32_e32 v12, v12
	v_exp_f32_e32 v10, v10
	v_cmp_nlt_f32_e32 vcc, s13, v9
	v_ldexp_f32 v10, v10, v12
	s_nop 0
	v_cndmask_b32_e32 v10, 0, v10, vcc
	v_cmp_ngt_f32_e32 vcc, s14, v9
	s_nop 1
	v_cndmask_b32_e32 v10, v91, v10, vcc
	v_add_f32_e32 v10, 1.0, v10
	v_div_scale_f32 v11, s[22:23], v10, v10, v9
	v_rcp_f32_e32 v13, v11
	v_div_scale_f32 v12, vcc, v9, v10, v9
	v_fma_f32 v14, -v11, v13, 1.0
	v_fmac_f32_e32 v13, v14, v13
	v_mul_f32_e32 v14, v12, v13
	v_fma_f32 v15, -v11, v14, v12
	v_fmac_f32_e32 v14, v15, v13
	v_fma_f32 v11, -v11, v14, v12
	v_div_fmas_f32 v11, v11, v13, v14
	v_div_fixup_f32 v9, v11, v10, v9
	ds_write_b32 v188, v9 offset:14336
	global_load_dword v6, v187, s[26:27]
	s_add_u32 s26, s26, 0x1000
	s_addc_u32 s27, s27, 0
	global_load_dword v7, v187, s[26:27]
	s_add_u32 s26, s26, 0x1000
	s_addc_u32 s27, s27, 0
	global_load_dword v8, v187, s[26:27]
	s_add_u32 s26, s26, 0x1000
	s_addc_u32 s27, s27, 0
	global_load_dword v9, v187, s[26:27]
	s_add_u32 s26, s26, 0x1000
	s_addc_u32 s27, s27, 0
	v_add_u32_e32 v188, 0x4000, v188
	s_add_i32 s28, s28, 1
	s_cmp_eq_u32 s28, 4
	s_cbranch_scc0 .Lpm_silu0
	s_waitcnt vmcnt(0)
	s_waitcnt lgkmcnt(0)
	s_barrier
.Lpm_loop:
	s_cmp_lg_u32 s24, 8
	s_cbranch_scc1 .Lpm_body
	s_barrier
	s_mov_b32 s26, s54
	s_mov_b32 s27, s55
	s_mov_b32 s28, 0
	v_mov_b32_e32 v188, v90
	global_load_dword v2, v187, s[26:27] offset:1024
	s_add_u32 s26, s26, 0x1000
	s_addc_u32 s27, s27, 0
	global_load_dword v3, v187, s[26:27] offset:1024
	s_add_u32 s26, s26, 0x1000
	s_addc_u32 s27, s27, 0
	global_load_dword v4, v187, s[26:27] offset:1024
	s_add_u32 s26, s26, 0x1000
	s_addc_u32 s27, s27, 0
	global_load_dword v5, v187, s[26:27] offset:1024
	s_add_u32 s26, s26, 0x1000
	s_addc_u32 s27, s27, 0
	global_load_dword v6, v187, s[26:27] offset:1024
	s_add_u32 s26, s26, 0x1000
	s_addc_u32 s27, s27, 0
	global_load_dword v7, v187, s[26:27] offset:1024
	s_add_u32 s26, s26, 0x1000
	s_addc_u32 s27, s27, 0
	global_load_dword v8, v187, s[26:27] offset:1024
	s_add_u32 s26, s26, 0x1000
	s_addc_u32 s27, s27, 0
	global_load_dword v9, v187, s[26:27] offset:1024
	s_add_u32 s26, s26, 0x1000
	s_addc_u32 s27, s27, 0
.Lpm_silu1:
	s_waitcnt vmcnt(4)
	v_mul_f32_e32 v10, 0xbfb8aa3b, v2
	v_fma_f32 v11, v2, s12, -v10
	v_rndne_f32_e32 v12, v10
	v_fmac_f32_e32 v11, 0xb2a5705f, v2
	v_sub_f32_e32 v10, v10, v12
	v_add_f32_e32 v10, v10, v11
	v_cvt_i32_f32_e32 v12, v12
	v_exp_f32_e32 v10, v10
	v_cmp_nlt_f32_e32 vcc, s13, v2
	v_ldexp_f32 v10, v10, v12
	s_nop 0
	v_cndmask_b32_e32 v10, 0, v10, vcc
	v_cmp_ngt_f32_e32 vcc, s14, v2
	s_nop 1
	v_cndmask_b32_e32 v10, v91, v10, vcc
	v_add_f32_e32 v10, 1.0, v10
	v_div_scale_f32 v11, s[22:23], v10, v10, v2
	v_rcp_f32_e32 v13, v11
	v_div_scale_f32 v12, vcc, v2, v10, v2
	v_fma_f32 v14, -v11, v13, 1.0
	v_fmac_f32_e32 v13, v14, v13
	v_mul_f32_e32 v14, v12, v13
	v_fma_f32 v15, -v11, v14, v12
	v_fmac_f32_e32 v14, v15, v13
	v_fma_f32 v11, -v11, v14, v12
	v_div_fmas_f32 v11, v11, v13, v14
	v_div_fixup_f32 v2, v11, v10, v2
	ds_write_b32 v188, v2
	v_mul_f32_e32 v10, 0xbfb8aa3b, v3
	v_fma_f32 v11, v3, s12, -v10
	v_rndne_f32_e32 v12, v10
	v_fmac_f32_e32 v11, 0xb2a5705f, v3
	v_sub_f32_e32 v10, v10, v12
	v_add_f32_e32 v10, v10, v11
	v_cvt_i32_f32_e32 v12, v12
	v_exp_f32_e32 v10, v10
	v_cmp_nlt_f32_e32 vcc, s13, v3
	v_ldexp_f32 v10, v10, v12
	s_nop 0
	v_cndmask_b32_e32 v10, 0, v10, vcc
	v_cmp_ngt_f32_e32 vcc, s14, v3
	s_nop 1
	v_cndmask_b32_e32 v10, v91, v10, vcc
	v_add_f32_e32 v10, 1.0, v10
	v_div_scale_f32 v11, s[22:23], v10, v10, v3
	v_rcp_f32_e32 v13, v11
	v_div_scale_f32 v12, vcc, v3, v10, v3
	v_fma_f32 v14, -v11, v13, 1.0
	v_fmac_f32_e32 v13, v14, v13
	v_mul_f32_e32 v14, v12, v13
	v_fma_f32 v15, -v11, v14, v12
	v_fmac_f32_e32 v14, v15, v13
	v_fma_f32 v11, -v11, v14, v12
	v_div_fmas_f32 v11, v11, v13, v14
	v_div_fixup_f32 v3, v11, v10, v3
	ds_write_b32 v188, v3 offset:2048
	v_mul_f32_e32 v10, 0xbfb8aa3b, v4
	v_fma_f32 v11, v4, s12, -v10
	v_rndne_f32_e32 v12, v10
	v_fmac_f32_e32 v11, 0xb2a5705f, v4
	v_sub_f32_e32 v10, v10, v12
	v_add_f32_e32 v10, v10, v11
	v_cvt_i32_f32_e32 v12, v12
	v_exp_f32_e32 v10, v10
	v_cmp_nlt_f32_e32 vcc, s13, v4
	v_ldexp_f32 v10, v10, v12
	s_nop 0
	v_cndmask_b32_e32 v10, 0, v10, vcc
	v_cmp_ngt_f32_e32 vcc, s14, v4
	s_nop 1
	v_cndmask_b32_e32 v10, v91, v10, vcc
	v_add_f32_e32 v10, 1.0, v10
	v_div_scale_f32 v11, s[22:23], v10, v10, v4
	v_rcp_f32_e32 v13, v11
	v_div_scale_f32 v12, vcc, v4, v10, v4
	v_fma_f32 v14, -v11, v13, 1.0
	v_fmac_f32_e32 v13, v14, v13
	v_mul_f32_e32 v14, v12, v13
	v_fma_f32 v15, -v11, v14, v12
	v_fmac_f32_e32 v14, v15, v13
	v_fma_f32 v11, -v11, v14, v12
	v_div_fmas_f32 v11, v11, v13, v14
	v_div_fixup_f32 v4, v11, v10, v4
	ds_write_b32 v188, v4 offset:4096
	v_mul_f32_e32 v10, 0xbfb8aa3b, v5
	v_fma_f32 v11, v5, s12, -v10
	v_rndne_f32_e32 v12, v10
	v_fmac_f32_e32 v11, 0xb2a5705f, v5
	v_sub_f32_e32 v10, v10, v12
	v_add_f32_e32 v10, v10, v11
	v_cvt_i32_f32_e32 v12, v12
	v_exp_f32_e32 v10, v10
	v_cmp_nlt_f32_e32 vcc, s13, v5
	v_ldexp_f32 v10, v10, v12
	s_nop 0
	v_cndmask_b32_e32 v10, 0, v10, vcc
	v_cmp_ngt_f32_e32 vcc, s14, v5
	s_nop 1
	v_cndmask_b32_e32 v10, v91, v10, vcc
	v_add_f32_e32 v10, 1.0, v10
	v_div_scale_f32 v11, s[22:23], v10, v10, v5
	v_rcp_f32_e32 v13, v11
	v_div_scale_f32 v12, vcc, v5, v10, v5
	v_fma_f32 v14, -v11, v13, 1.0
	v_fmac_f32_e32 v13, v14, v13
	v_mul_f32_e32 v14, v12, v13
	v_fma_f32 v15, -v11, v14, v12
	v_fmac_f32_e32 v14, v15, v13
	v_fma_f32 v11, -v11, v14, v12
	v_div_fmas_f32 v11, v11, v13, v14
	v_div_fixup_f32 v5, v11, v10, v5
	ds_write_b32 v188, v5 offset:6144
	s_cmp_eq_u32 s28, 3
	s_cselect_b32 s26, s54, s26
	s_cselect_b32 s27, s55, s27
	global_load_dword v2, v187, s[26:27] offset:1024
	s_add_u32 s26, s26, 0x1000
	s_addc_u32 s27, s27, 0
	global_load_dword v3, v187, s[26:27] offset:1024
	s_add_u32 s26, s26, 0x1000
	s_addc_u32 s27, s27, 0
	global_load_dword v4, v187, s[26:27] offset:1024
	s_add_u32 s26, s26, 0x1000
	s_addc_u32 s27, s27, 0
	global_load_dword v5, v187, s[26:27] offset:1024
	s_add_u32 s26, s26, 0x1000
	s_addc_u32 s27, s27, 0
	s_waitcnt vmcnt(4)
; __device__ NOINL void prep_mod(const float* c, const float* wada, const float* bada, float* mod, LAS unsigned char* lds, int wv) {
;     ...
;             for (int kk = 0; kk < 256; ++kk) { const float w = wp[(size_t)kk * 12288];
; #pragma unroll
;                 for (int b = 0; b < 16; ++b) acc[b] += cs[b * 1024 + kq * 256 + kk] * w; }
	v_mul_f32_e32 v10, 0xbfb8aa3b, v6
	v_fma_f32 v11, v6, s12, -v10
	v_rndne_f32_e32 v12, v10
	v_fmac_f32_e32 v11, 0xb2a5705f, v6
	v_sub_f32_e32 v10, v10, v12
	v_add_f32_e32 v10, v10, v11
	v_cvt_i32_f32_e32 v12, v12
	v_exp_f32_e32 v10, v10
	v_cmp_nlt_f32_e32 vcc, s13, v6
	v_ldexp_f32 v10, v10, v12
	s_nop 0
	v_cndmask_b32_e32 v10, 0, v10, vcc
	v_cmp_ngt_f32_e32 vcc, s14, v6
	s_nop 1
	v_cndmask_b32_e32 v10, v91, v10, vcc
	v_add_f32_e32 v10, 1.0, v10
	v_div_scale_f32 v11, s[22:23], v10, v10, v6
	v_rcp_f32_e32 v13, v11
	v_div_scale_f32 v12, vcc, v6, v10, v6
	v_fma_f32 v14, -v11, v13, 1.0
	v_fmac_f32_e32 v13, v14, v13
	v_mul_f32_e32 v14, v12, v13
	v_fma_f32 v15, -v11, v14, v12
	v_fmac_f32_e32 v14, v15, v13
	v_fma_f32 v11, -v11, v14, v12
	v_div_fmas_f32 v11, v11, v13, v14
	v_div_fixup_f32 v6, v11, v10, v6
	ds_write_b32 v188, v6 offset:8192
	v_mul_f32_e32 v10, 0xbfb8aa3b, v7
	v_fma_f32 v11, v7, s12, -v10
	v_rndne_f32_e32 v12, v10
	v_fmac_f32_e32 v11, 0xb2a5705f, v7
	v_sub_f32_e32 v10, v10, v12
	v_add_f32_e32 v10, v10, v11
	v_cvt_i32_f32_e32 v12, v12
	v_exp_f32_e32 v10, v10
	v_cmp_nlt_f32_e32 vcc, s13, v7
	v_ldexp_f32 v10, v10, v12
	s_nop 0
	v_cndmask_b32_e32 v10, 0, v10, vcc
	v_cmp_ngt_f32_e32 vcc, s14, v7
	s_nop 1
	v_cndmask_b32_e32 v10, v91, v10, vcc
	v_add_f32_e32 v10, 1.0, v10
	v_div_scale_f32 v11, s[22:23], v10, v10, v7
	v_rcp_f32_e32 v13, v11
	v_div_scale_f32 v12, vcc, v7, v10, v7
	v_fma_f32 v14, -v11, v13, 1.0
	v_fmac_f32_e32 v13, v14, v13
	v_mul_f32_e32 v14, v12, v13
	v_fma_f32 v15, -v11, v14, v12
	v_fmac_f32_e32 v14, v15, v13
	v_fma_f32 v11, -v11, v14, v12
	v_div_fmas_f32 v11, v11, v13, v14
	v_div_fixup_f32 v7, v11, v10, v7
	ds_write_b32 v188, v7 offset:10240
	v_mul_f32_e32 v10, 0xbfb8aa3b, v8
	v_fma_f32 v11, v8, s12, -v10
	v_rndne_f32_e32 v12, v10
	v_fmac_f32_e32 v11, 0xb2a5705f, v8
	v_sub_f32_e32 v10, v10, v12
	v_add_f32_e32 v10, v10, v11
	v_cvt_i32_f32_e32 v12, v12
	v_exp_f32_e32 v10, v10
	v_cmp_nlt_f32_e32 vcc, s13, v8
	v_ldexp_f32 v10, v10, v12
	s_nop 0
	v_cndmask_b32_e32 v10, 0, v10, vcc
	v_cmp_ngt_f32_e32 vcc, s14, v8
	s_nop 1
	v_cndmask_b32_e32 v10, v91, v10, vcc
	v_add_f32_e32 v10, 1.0, v10
	v_div_scale_f32 v11, s[22:23], v10, v10, v8
	v_rcp_f32_e32 v13, v11
	v_div_scale_f32 v12, vcc, v8, v10, v8
	v_fma_f32 v14, -v11, v13, 1.0
	v_fmac_f32_e32 v13, v14, v13
	v_mul_f32_e32 v14, v12, v13
	v_fma_f32 v15, -v11, v14, v12
	v_fmac_f32_e32 v14, v15, v13
	v_fma_f32 v11, -v11, v14, v12
	v_div_fmas_f32 v11, v11, v13, v14
	v_div_fixup_f32 v8, v11, v10, v8
	ds_write_b32 v188, v8 offset:12288
	v_mul_f32_e32 v10, 0xbfb8aa3b, v9
	v_fma_f32 v11, v9, s12, -v10
	v_rndne_f32_e32 v12, v10
	v_fmac_f32_e32 v11, 0xb2a5705f, v9
	v_sub_f32_e32 v10, v10, v12
	v_add_f32_e32 v10, v10, v11
	v_cvt_i32_f32_e32 v12, v12
	v_exp_f32_e32 v10, v10
	v_cmp_nlt_f32_e32 vcc, s13, v9
	v_ldexp_f32 v10, v10, v12
	s_nop 0
	v_cndmask_b32_e32 v10, 0, v10, vcc
	v_cmp_ngt_f32_e32 vcc, s14, v9
	s_nop 1
	v_cndmask_b32_e32 v10, v91, v10, vcc
	v_add_f32_e32 v10, 1.0, v10
	v_div_scale_f32 v11, s[22:23], v10, v10, v9
	v_rcp_f32_e32 v13, v11
	v_div_scale_f32 v12, vcc, v9, v10, v9
	v_fma_f32 v14, -v11, v13, 1.0
	v_fmac_f32_e32 v13, v14, v13
	v_mul_f32_e32 v14, v12, v13
	v_fma_f32 v15, -v11, v14, v12
	v_fmac_f32_e32 v14, v15, v13
	v_fma_f32 v11, -v11, v14, v12
	v_div_fmas_f32 v11, v11, v13, v14
	v_div_fixup_f32 v9, v11, v10, v9
	ds_write_b32 v188, v9 offset:14336
	global_load_dword v6, v187, s[26:27] offset:1024
	s_add_u32 s26, s26, 0x1000
	s_addc_u32 s27, s27, 0
	global_load_dword v7, v187, s[26:27] offset:1024
	s_add_u32 s26, s26, 0x1000
	s_addc_u32 s27, s27, 0
	global_load_dword v8, v187, s[26:27] offset:1024
	s_add_u32 s26, s26, 0x1000
	s_addc_u32 s27, s27, 0
	global_load_dword v9, v187, s[26:27] offset:1024
	s_add_u32 s26, s26, 0x1000
	s_addc_u32 s27, s27, 0
	v_add_u32_e32 v188, 0x4000, v188
	s_add_i32 s28, s28, 1
	s_cmp_eq_u32 s28, 4
	s_cbranch_scc0 .Lpm_silu1
	s_waitcnt vmcnt(0)
	s_waitcnt lgkmcnt(0)
	s_barrier
	v_mov_b32_e32 v93, v80
.Lpm_body:
	global_load_dword v122, v186, s[8:9]
	s_add_u32 s8, s8, 0xc000
	s_addc_u32 s9, s9, 0
	global_load_dword v123, v186, s[8:9]
	s_add_u32 s8, s8, 0xc000
	s_addc_u32 s9, s9, 0
	global_load_dword v124, v186, s[8:9]
	s_add_u32 s8, s8, 0xc000
	s_addc_u32 s9, s9, 0
	global_load_dword v125, v186, s[8:9]
	s_add_u32 s8, s8, 0xc000
	s_addc_u32 s9, s9, 0
	ds_read_b128 v[2:5], v93 offset:0
	ds_read_b128 v[6:9], v93 offset:4096
	ds_read_b128 v[10:13], v93 offset:8192
	ds_read_b128 v[14:17], v93 offset:12288
	ds_read_b128 v[18:21], v93 offset:16384
	ds_read_b128 v[22:25], v93 offset:20480
	ds_read_b128 v[26:29], v93 offset:24576
	ds_read_b128 v[30:33], v93 offset:28672
	ds_read_b128 v[34:37], v93 offset:32768
	ds_read_b128 v[38:41], v93 offset:36864
	ds_read_b128 v[42:45], v93 offset:40960
	ds_read_b128 v[126:129], v93 offset:45056
	ds_read_b128 v[130:133], v93 offset:49152
	ds_read_b128 v[134:137], v93 offset:53248
	ds_read_b128 v[138:141], v93 offset:57344
	ds_read_b128 v[142:145], v93 offset:61440
	s_waitcnt vmcnt(28)
	s_waitcnt lgkmcnt(8)
	v_pk_fma_f32 v[146:147], v[2:3], v[94:95], v[146:147]
	v_pk_fma_f32 v[148:149], v[6:7], v[94:95], v[148:149]
	v_pk_fma_f32 v[150:151], v[10:11], v[94:95], v[150:151]
	v_pk_fma_f32 v[152:153], v[14:15], v[94:95], v[152:153]
	v_pk_fma_f32 v[154:155], v[18:19], v[94:95], v[154:155]
	v_pk_fma_f32 v[156:157], v[22:23], v[94:95], v[156:157]
	v_pk_fma_f32 v[158:159], v[26:27], v[94:95], v[158:159]
	v_pk_fma_f32 v[168:169], v[30:31], v[94:95], v[168:169]
	v_pk_fma_f32 v[146:147], v[4:5], v[96:97], v[146:147]
	v_pk_fma_f32 v[148:149], v[8:9], v[96:97], v[148:149]
	v_pk_fma_f32 v[150:151], v[12:13], v[96:97], v[150:151]
	v_pk_fma_f32 v[152:153], v[16:17], v[96:97], v[152:153]
	v_pk_fma_f32 v[154:155], v[20:21], v[96:97], v[154:155]
	v_pk_fma_f32 v[156:157], v[24:25], v[96:97], v[156:157]
	v_pk_fma_f32 v[158:159], v[28:29], v[96:97], v[158:159]
	v_pk_fma_f32 v[168:169], v[32:33], v[96:97], v[168:169]
	s_waitcnt lgkmcnt(0)
; __device__ NOINL void prep_mod(const float* c, const float* wada, const float* bada, float* mod, LAS unsigned char* lds, int wv) {
;     ...
;             for (int kk = 0; kk < 256; ++kk) { const float w = wp[(size_t)kk * 12288];
; #pragma unroll
;                 for (int b = 0; b < 16; ++b) acc[b] += cs[b * 1024 + kq * 256 + kk] * w; }
	v_pk_fma_f32 v[170:171], v[34:35], v[94:95], v[170:171]
	v_pk_fma_f32 v[172:173], v[38:39], v[94:95], v[172:173]
	v_pk_fma_f32 v[174:175], v[42:43], v[94:95], v[174:175]
	v_pk_fma_f32 v[176:177], v[126:127], v[94:95], v[176:177]
	v_pk_fma_f32 v[178:179], v[130:131], v[94:95], v[178:179]
	v_pk_fma_f32 v[180:181], v[134:135], v[94:95], v[180:181]
	v_pk_fma_f32 v[182:183], v[138:139], v[94:95], v[182:183]
	v_pk_fma_f32 v[184:185], v[142:143], v[94:95], v[184:185]
	v_pk_fma_f32 v[170:171], v[36:37], v[96:97], v[170:171]
	v_pk_fma_f32 v[172:173], v[40:41], v[96:97], v[172:173]
	v_pk_fma_f32 v[174:175], v[44:45], v[96:97], v[174:175]
	v_pk_fma_f32 v[176:177], v[128:129], v[96:97], v[176:177]
	v_pk_fma_f32 v[178:179], v[132:133], v[96:97], v[178:179]
	v_pk_fma_f32 v[180:181], v[136:137], v[96:97], v[180:181]
	v_pk_fma_f32 v[182:183], v[140:141], v[96:97], v[182:183]
	v_pk_fma_f32 v[184:185], v[144:145], v[96:97], v[184:185]
	s_cmp_eq_u32 s24, 15
	s_cselect_b32 s8, s29, s8
	s_cselect_b32 s9, s30, s9
	global_load_dword v94, v186, s[8:9]
	s_add_u32 s8, s8, 0xc000
	s_addc_u32 s9, s9, 0
	global_load_dword v95, v186, s[8:9]
	s_add_u32 s8, s8, 0xc000
	s_addc_u32 s9, s9, 0
	global_load_dword v96, v186, s[8:9]
	s_add_u32 s8, s8, 0xc000
	s_addc_u32 s9, s9, 0
	global_load_dword v97, v186, s[8:9]
	s_add_u32 s8, s8, 0xc000
	s_addc_u32 s9, s9, 0
	ds_read_b128 v[2:5], v93 offset:16
	ds_read_b128 v[6:9], v93 offset:4112
	ds_read_b128 v[10:13], v93 offset:8208
	ds_read_b128 v[14:17], v93 offset:12304
	ds_read_b128 v[18:21], v93 offset:16400
	ds_read_b128 v[22:25], v93 offset:20496
	ds_read_b128 v[26:29], v93 offset:24592
	ds_read_b128 v[30:33], v93 offset:28688
	ds_read_b128 v[34:37], v93 offset:32784
	ds_read_b128 v[38:41], v93 offset:36880
	ds_read_b128 v[42:45], v93 offset:40976
	ds_read_b128 v[126:129], v93 offset:45072
	ds_read_b128 v[130:133], v93 offset:49168
	ds_read_b128 v[134:137], v93 offset:53264
	ds_read_b128 v[138:141], v93 offset:57360
	ds_read_b128 v[142:145], v93 offset:61456
	s_waitcnt vmcnt(28)
	s_waitcnt lgkmcnt(8)
	v_pk_fma_f32 v[146:147], v[2:3], v[98:99], v[146:147]
	v_pk_fma_f32 v[148:149], v[6:7], v[98:99], v[148:149]
	v_pk_fma_f32 v[150:151], v[10:11], v[98:99], v[150:151]
	v_pk_fma_f32 v[152:153], v[14:15], v[98:99], v[152:153]
	v_pk_fma_f32 v[154:155], v[18:19], v[98:99], v[154:155]
	v_pk_fma_f32 v[156:157], v[22:23], v[98:99], v[156:157]
	v_pk_fma_f32 v[158:159], v[26:27], v[98:99], v[158:159]
	v_pk_fma_f32 v[168:169], v[30:31], v[98:99], v[168:169]
	v_pk_fma_f32 v[146:147], v[4:5], v[100:101], v[146:147]
	v_pk_fma_f32 v[148:149], v[8:9], v[100:101], v[148:149]
	v_pk_fma_f32 v[150:151], v[12:13], v[100:101], v[150:151]
	v_pk_fma_f32 v[152:153], v[16:17], v[100:101], v[152:153]
	v_pk_fma_f32 v[154:155], v[20:21], v[100:101], v[154:155]
	v_pk_fma_f32 v[156:157], v[24:25], v[100:101], v[156:157]
	v_pk_fma_f32 v[158:159], v[28:29], v[100:101], v[158:159]
	v_pk_fma_f32 v[168:169], v[32:33], v[100:101], v[168:169]
	s_waitcnt lgkmcnt(0)
	v_pk_fma_f32 v[170:171], v[34:35], v[98:99], v[170:171]
	v_pk_fma_f32 v[172:173], v[38:39], v[98:99], v[172:173]
	v_pk_fma_f32 v[174:175], v[42:43], v[98:99], v[174:175]
	v_pk_fma_f32 v[176:177], v[126:127], v[98:99], v[176:177]
	v_pk_fma_f32 v[178:179], v[130:131], v[98:99], v[178:179]
	v_pk_fma_f32 v[180:181], v[134:135], v[98:99], v[180:181]
	v_pk_fma_f32 v[182:183], v[138:139], v[98:99], v[182:183]
	v_pk_fma_f32 v[184:185], v[142:143], v[98:99], v[184:185]
	v_pk_fma_f32 v[170:171], v[36:37], v[100:101], v[170:171]
	v_pk_fma_f32 v[172:173], v[40:41], v[100:101], v[172:173]
	v_pk_fma_f32 v[174:175], v[44:45], v[100:101], v[174:175]
	v_pk_fma_f32 v[176:177], v[128:129], v[100:101], v[176:177]
	v_pk_fma_f32 v[178:179], v[132:133], v[100:101], v[178:179]
	v_pk_fma_f32 v[180:181], v[136:137], v[100:101], v[180:181]
	v_pk_fma_f32 v[182:183], v[140:141], v[100:101], v[182:183]
	v_pk_fma_f32 v[184:185], v[144:145], v[100:101], v[184:185]
	global_load_dword v98, v186, s[8:9]
	s_add_u32 s8, s8, 0xc000
	s_addc_u32 s9, s9, 0
	global_load_dword v99, v186, s[8:9]
	s_add_u32 s8, s8, 0xc000
	s_addc_u32 s9, s9, 0
	global_load_dword v100, v186, s[8:9]
	s_add_u32 s8, s8, 0xc000
	s_addc_u32 s9, s9, 0
	global_load_dword v101, v186, s[8:9]
	s_add_u32 s8, s8, 0xc000
	s_addc_u32 s9, s9, 0
	ds_read_b128 v[2:5], v93 offset:32
	ds_read_b128 v[6:9], v93 offset:4128
	ds_read_b128 v[10:13], v93 offset:8224
	ds_read_b128 v[14:17], v93 offset:12320
	ds_read_b128 v[18:21], v93 offset:16416
	ds_read_b128 v[22:25], v93 offset:20512
	ds_read_b128 v[26:29], v93 offset:24608
	ds_read_b128 v[30:33], v93 offset:28704
	ds_read_b128 v[34:37], v93 offset:32800
	ds_read_b128 v[38:41], v93 offset:36896
	ds_read_b128 v[42:45], v93 offset:40992
	ds_read_b128 v[126:129], v93 offset:45088
	ds_read_b128 v[130:133], v93 offset:49184
	ds_read_b128 v[134:137], v93 offset:53280
	ds_read_b128 v[138:141], v93 offset:57376
	ds_read_b128 v[142:145], v93 offset:61472
	s_waitcnt vmcnt(28)
	s_waitcnt lgkmcnt(8)
	v_pk_fma_f32 v[146:147], v[2:3], v[102:103], v[146:147]
	v_pk_fma_f32 v[148:149], v[6:7], v[102:103], v[148:149]
	v_pk_fma_f32 v[150:151], v[10:11], v[102:103], v[150:151]
	v_pk_fma_f32 v[152:153], v[14:15], v[102:103], v[152:153]
	v_pk_fma_f32 v[154:155], v[18:19], v[102:103], v[154:155]
	v_pk_fma_f32 v[156:157], v[22:23], v[102:103], v[156:157]
	v_pk_fma_f32 v[158:159], v[26:27], v[102:103], v[158:159]
	v_pk_fma_f32 v[168:169], v[30:31], v[102:103], v[168:169]
	v_pk_fma_f32 v[146:147], v[4:5], v[104:105], v[146:147]
	v_pk_fma_f32 v[148:149], v[8:9], v[104:105], v[148:149]
	v_pk_fma_f32 v[150:151], v[12:13], v[104:105], v[150:151]
	v_pk_fma_f32 v[152:153], v[16:17], v[104:105], v[152:153]
	v_pk_fma_f32 v[154:155], v[20:21], v[104:105], v[154:155]
	v_pk_fma_f32 v[156:157], v[24:25], v[104:105], v[156:157]
	v_pk_fma_f32 v[158:159], v[28:29], v[104:105], v[158:159]
	v_pk_fma_f32 v[168:169], v[32:33], v[104:105], v[168:169]
	s_waitcnt lgkmcnt(0)
; __device__ NOINL void prep_mod(const float* c, const float* wada, const float* bada, float* mod, LAS unsigned char* lds, int wv) {
;     ...
;             for (int kk = 0; kk < 256; ++kk) { const float w = wp[(size_t)kk * 12288];
; #pragma unroll
;                 for (int b = 0; b < 16; ++b) acc[b] += cs[b * 1024 + kq * 256 + kk] * w; }
	v_pk_fma_f32 v[170:171], v[34:35], v[102:103], v[170:171]
	v_pk_fma_f32 v[172:173], v[38:39], v[102:103], v[172:173]
	v_pk_fma_f32 v[174:175], v[42:43], v[102:103], v[174:175]
	v_pk_fma_f32 v[176:177], v[126:127], v[102:103], v[176:177]
	v_pk_fma_f32 v[178:179], v[130:131], v[102:103], v[178:179]
	v_pk_fma_f32 v[180:181], v[134:135], v[102:103], v[180:181]
	v_pk_fma_f32 v[182:183], v[138:139], v[102:103], v[182:183]
	v_pk_fma_f32 v[184:185], v[142:143], v[102:103], v[184:185]
	v_pk_fma_f32 v[170:171], v[36:37], v[104:105], v[170:171]
	v_pk_fma_f32 v[172:173], v[40:41], v[104:105], v[172:173]
	v_pk_fma_f32 v[174:175], v[44:45], v[104:105], v[174:175]
	v_pk_fma_f32 v[176:177], v[128:129], v[104:105], v[176:177]
	v_pk_fma_f32 v[178:179], v[132:133], v[104:105], v[178:179]
	v_pk_fma_f32 v[180:181], v[136:137], v[104:105], v[180:181]
	v_pk_fma_f32 v[182:183], v[140:141], v[104:105], v[182:183]
	v_pk_fma_f32 v[184:185], v[144:145], v[104:105], v[184:185]
	global_load_dword v102, v186, s[8:9]
	s_add_u32 s8, s8, 0xc000
	s_addc_u32 s9, s9, 0
	global_load_dword v103, v186, s[8:9]
	s_add_u32 s8, s8, 0xc000
	s_addc_u32 s9, s9, 0
	global_load_dword v104, v186, s[8:9]
	s_add_u32 s8, s8, 0xc000
	s_addc_u32 s9, s9, 0
	global_load_dword v105, v186, s[8:9]
	s_add_u32 s8, s8, 0xc000
	s_addc_u32 s9, s9, 0
	ds_read_b128 v[2:5], v93 offset:48
	ds_read_b128 v[6:9], v93 offset:4144
	ds_read_b128 v[10:13], v93 offset:8240
	ds_read_b128 v[14:17], v93 offset:12336
	ds_read_b128 v[18:21], v93 offset:16432
	ds_read_b128 v[22:25], v93 offset:20528
	ds_read_b128 v[26:29], v93 offset:24624
	ds_read_b128 v[30:33], v93 offset:28720
	ds_read_b128 v[34:37], v93 offset:32816
	ds_read_b128 v[38:41], v93 offset:36912
	ds_read_b128 v[42:45], v93 offset:41008
	ds_read_b128 v[126:129], v93 offset:45104
	ds_read_b128 v[130:133], v93 offset:49200
	ds_read_b128 v[134:137], v93 offset:53296
	ds_read_b128 v[138:141], v93 offset:57392
	ds_read_b128 v[142:145], v93 offset:61488
	s_waitcnt vmcnt(28)
	s_waitcnt lgkmcnt(8)
	v_pk_fma_f32 v[146:147], v[2:3], v[106:107], v[146:147]
	v_pk_fma_f32 v[148:149], v[6:7], v[106:107], v[148:149]
	v_pk_fma_f32 v[150:151], v[10:11], v[106:107], v[150:151]
	v_pk_fma_f32 v[152:153], v[14:15], v[106:107], v[152:153]
	v_pk_fma_f32 v[154:155], v[18:19], v[106:107], v[154:155]
	v_pk_fma_f32 v[156:157], v[22:23], v[106:107], v[156:157]
	v_pk_fma_f32 v[158:159], v[26:27], v[106:107], v[158:159]
	v_pk_fma_f32 v[168:169], v[30:31], v[106:107], v[168:169]
	v_pk_fma_f32 v[146:147], v[4:5], v[108:109], v[146:147]
	v_pk_fma_f32 v[148:149], v[8:9], v[108:109], v[148:149]
	v_pk_fma_f32 v[150:151], v[12:13], v[108:109], v[150:151]
	v_pk_fma_f32 v[152:153], v[16:17], v[108:109], v[152:153]
	v_pk_fma_f32 v[154:155], v[20:21], v[108:109], v[154:155]
	v_pk_fma_f32 v[156:157], v[24:25], v[108:109], v[156:157]
	v_pk_fma_f32 v[158:159], v[28:29], v[108:109], v[158:159]
	v_pk_fma_f32 v[168:169], v[32:33], v[108:109], v[168:169]
	s_waitcnt lgkmcnt(0)
	v_pk_fma_f32 v[170:171], v[34:35], v[106:107], v[170:171]
	v_pk_fma_f32 v[172:173], v[38:39], v[106:107], v[172:173]
	v_pk_fma_f32 v[174:175], v[42:43], v[106:107], v[174:175]
	v_pk_fma_f32 v[176:177], v[126:127], v[106:107], v[176:177]
	v_pk_fma_f32 v[178:179], v[130:131], v[106:107], v[178:179]
	v_pk_fma_f32 v[180:181], v[134:135], v[106:107], v[180:181]
	v_pk_fma_f32 v[182:183], v[138:139], v[106:107], v[182:183]
	v_pk_fma_f32 v[184:185], v[142:143], v[106:107], v[184:185]
	v_pk_fma_f32 v[170:171], v[36:37], v[108:109], v[170:171]
	v_pk_fma_f32 v[172:173], v[40:41], v[108:109], v[172:173]
	v_pk_fma_f32 v[174:175], v[44:45], v[108:109], v[174:175]
	v_pk_fma_f32 v[176:177], v[128:129], v[108:109], v[176:177]
	v_pk_fma_f32 v[178:179], v[132:133], v[108:109], v[178:179]
	v_pk_fma_f32 v[180:181], v[136:137], v[108:109], v[180:181]
	v_pk_fma_f32 v[182:183], v[140:141], v[108:109], v[182:183]
	v_pk_fma_f32 v[184:185], v[144:145], v[108:109], v[184:185]
	global_load_dword v106, v186, s[8:9]
	s_add_u32 s8, s8, 0xc000
	s_addc_u32 s9, s9, 0
	global_load_dword v107, v186, s[8:9]
	s_add_u32 s8, s8, 0xc000
	s_addc_u32 s9, s9, 0
	global_load_dword v108, v186, s[8:9]
	s_add_u32 s8, s8, 0xc000
	s_addc_u32 s9, s9, 0
	global_load_dword v109, v186, s[8:9]
	s_add_u32 s8, s8, 0xc000
	s_addc_u32 s9, s9, 0
	ds_read_b128 v[2:5], v93 offset:64
	ds_read_b128 v[6:9], v93 offset:4160
	ds_read_b128 v[10:13], v93 offset:8256
	ds_read_b128 v[14:17], v93 offset:12352
	ds_read_b128 v[18:21], v93 offset:16448
	ds_read_b128 v[22:25], v93 offset:20544
	ds_read_b128 v[26:29], v93 offset:24640
	ds_read_b128 v[30:33], v93 offset:28736
	ds_read_b128 v[34:37], v93 offset:32832
	ds_read_b128 v[38:41], v93 offset:36928
	ds_read_b128 v[42:45], v93 offset:41024
	ds_read_b128 v[126:129], v93 offset:45120
	ds_read_b128 v[130:133], v93 offset:49216
	ds_read_b128 v[134:137], v93 offset:53312
	ds_read_b128 v[138:141], v93 offset:57408
	ds_read_b128 v[142:145], v93 offset:61504
	s_waitcnt vmcnt(28)
	s_waitcnt lgkmcnt(8)
	v_pk_fma_f32 v[146:147], v[2:3], v[110:111], v[146:147]
	v_pk_fma_f32 v[148:149], v[6:7], v[110:111], v[148:149]
	v_pk_fma_f32 v[150:151], v[10:11], v[110:111], v[150:151]
	v_pk_fma_f32 v[152:153], v[14:15], v[110:111], v[152:153]
	v_pk_fma_f32 v[154:155], v[18:19], v[110:111], v[154:155]
	v_pk_fma_f32 v[156:157], v[22:23], v[110:111], v[156:157]
	v_pk_fma_f32 v[158:159], v[26:27], v[110:111], v[158:159]
	v_pk_fma_f32 v[168:169], v[30:31], v[110:111], v[168:169]
	v_pk_fma_f32 v[146:147], v[4:5], v[112:113], v[146:147]
	v_pk_fma_f32 v[148:149], v[8:9], v[112:113], v[148:149]
	v_pk_fma_f32 v[150:151], v[12:13], v[112:113], v[150:151]
	v_pk_fma_f32 v[152:153], v[16:17], v[112:113], v[152:153]
	v_pk_fma_f32 v[154:155], v[20:21], v[112:113], v[154:155]
	v_pk_fma_f32 v[156:157], v[24:25], v[112:113], v[156:157]
	v_pk_fma_f32 v[158:159], v[28:29], v[112:113], v[158:159]
	v_pk_fma_f32 v[168:169], v[32:33], v[112:113], v[168:169]
	s_waitcnt lgkmcnt(0)
; __device__ NOINL void prep_mod(const float* c, const float* wada, const float* bada, float* mod, LAS unsigned char* lds, int wv) {
;     ...
;             for (int kk = 0; kk < 256; ++kk) { const float w = wp[(size_t)kk * 12288];
; #pragma unroll
;                 for (int b = 0; b < 16; ++b) acc[b] += cs[b * 1024 + kq * 256 + kk] * w; }
	v_pk_fma_f32 v[170:171], v[34:35], v[110:111], v[170:171]
	v_pk_fma_f32 v[172:173], v[38:39], v[110:111], v[172:173]
	v_pk_fma_f32 v[174:175], v[42:43], v[110:111], v[174:175]
	v_pk_fma_f32 v[176:177], v[126:127], v[110:111], v[176:177]
	v_pk_fma_f32 v[178:179], v[130:131], v[110:111], v[178:179]
	v_pk_fma_f32 v[180:181], v[134:135], v[110:111], v[180:181]
	v_pk_fma_f32 v[182:183], v[138:139], v[110:111], v[182:183]
	v_pk_fma_f32 v[184:185], v[142:143], v[110:111], v[184:185]
	v_pk_fma_f32 v[170:171], v[36:37], v[112:113], v[170:171]
	v_pk_fma_f32 v[172:173], v[40:41], v[112:113], v[172:173]
	v_pk_fma_f32 v[174:175], v[44:45], v[112:113], v[174:175]
	v_pk_fma_f32 v[176:177], v[128:129], v[112:113], v[176:177]
	v_pk_fma_f32 v[178:179], v[132:133], v[112:113], v[178:179]
	v_pk_fma_f32 v[180:181], v[136:137], v[112:113], v[180:181]
	v_pk_fma_f32 v[182:183], v[140:141], v[112:113], v[182:183]
	v_pk_fma_f32 v[184:185], v[144:145], v[112:113], v[184:185]
	global_load_dword v110, v186, s[8:9]
	s_add_u32 s8, s8, 0xc000
	s_addc_u32 s9, s9, 0
	global_load_dword v111, v186, s[8:9]
	s_add_u32 s8, s8, 0xc000
	s_addc_u32 s9, s9, 0
	global_load_dword v112, v186, s[8:9]
	s_add_u32 s8, s8, 0xc000
	s_addc_u32 s9, s9, 0
	global_load_dword v113, v186, s[8:9]
	s_add_u32 s8, s8, 0xc000
	s_addc_u32 s9, s9, 0
	ds_read_b128 v[2:5], v93 offset:80
	ds_read_b128 v[6:9], v93 offset:4176
	ds_read_b128 v[10:13], v93 offset:8272
	ds_read_b128 v[14:17], v93 offset:12368
	ds_read_b128 v[18:21], v93 offset:16464
	ds_read_b128 v[22:25], v93 offset:20560
	ds_read_b128 v[26:29], v93 offset:24656
	ds_read_b128 v[30:33], v93 offset:28752
	ds_read_b128 v[34:37], v93 offset:32848
	ds_read_b128 v[38:41], v93 offset:36944
	ds_read_b128 v[42:45], v93 offset:41040
	ds_read_b128 v[126:129], v93 offset:45136
	ds_read_b128 v[130:133], v93 offset:49232
	ds_read_b128 v[134:137], v93 offset:53328
	ds_read_b128 v[138:141], v93 offset:57424
	ds_read_b128 v[142:145], v93 offset:61520
	s_waitcnt vmcnt(28)
	s_waitcnt lgkmcnt(8)
	v_pk_fma_f32 v[146:147], v[2:3], v[114:115], v[146:147]
	v_pk_fma_f32 v[148:149], v[6:7], v[114:115], v[148:149]
	v_pk_fma_f32 v[150:151], v[10:11], v[114:115], v[150:151]
	v_pk_fma_f32 v[152:153], v[14:15], v[114:115], v[152:153]
	v_pk_fma_f32 v[154:155], v[18:19], v[114:115], v[154:155]
	v_pk_fma_f32 v[156:157], v[22:23], v[114:115], v[156:157]
	v_pk_fma_f32 v[158:159], v[26:27], v[114:115], v[158:159]
	v_pk_fma_f32 v[168:169], v[30:31], v[114:115], v[168:169]
	v_pk_fma_f32 v[146:147], v[4:5], v[116:117], v[146:147]
	v_pk_fma_f32 v[148:149], v[8:9], v[116:117], v[148:149]
	v_pk_fma_f32 v[150:151], v[12:13], v[116:117], v[150:151]
	v_pk_fma_f32 v[152:153], v[16:17], v[116:117], v[152:153]
	v_pk_fma_f32 v[154:155], v[20:21], v[116:117], v[154:155]
	v_pk_fma_f32 v[156:157], v[24:25], v[116:117], v[156:157]
	v_pk_fma_f32 v[158:159], v[28:29], v[116:117], v[158:159]
	v_pk_fma_f32 v[168:169], v[32:33], v[116:117], v[168:169]
	s_waitcnt lgkmcnt(0)
	v_pk_fma_f32 v[170:171], v[34:35], v[114:115], v[170:171]
	v_pk_fma_f32 v[172:173], v[38:39], v[114:115], v[172:173]
	v_pk_fma_f32 v[174:175], v[42:43], v[114:115], v[174:175]
	v_pk_fma_f32 v[176:177], v[126:127], v[114:115], v[176:177]
	v_pk_fma_f32 v[178:179], v[130:131], v[114:115], v[178:179]
	v_pk_fma_f32 v[180:181], v[134:135], v[114:115], v[180:181]
	v_pk_fma_f32 v[182:183], v[138:139], v[114:115], v[182:183]
	v_pk_fma_f32 v[184:185], v[142:143], v[114:115], v[184:185]
	v_pk_fma_f32 v[170:171], v[36:37], v[116:117], v[170:171]
	v_pk_fma_f32 v[172:173], v[40:41], v[116:117], v[172:173]
	v_pk_fma_f32 v[174:175], v[44:45], v[116:117], v[174:175]
	v_pk_fma_f32 v[176:177], v[128:129], v[116:117], v[176:177]
	v_pk_fma_f32 v[178:179], v[132:133], v[116:117], v[178:179]
	v_pk_fma_f32 v[180:181], v[136:137], v[116:117], v[180:181]
	v_pk_fma_f32 v[182:183], v[140:141], v[116:117], v[182:183]
	v_pk_fma_f32 v[184:185], v[144:145], v[116:117], v[184:185]
	global_load_dword v114, v186, s[8:9]
	s_add_u32 s8, s8, 0xc000
	s_addc_u32 s9, s9, 0
	global_load_dword v115, v186, s[8:9]
	s_add_u32 s8, s8, 0xc000
	s_addc_u32 s9, s9, 0
	global_load_dword v116, v186, s[8:9]
	s_add_u32 s8, s8, 0xc000
	s_addc_u32 s9, s9, 0
	global_load_dword v117, v186, s[8:9]
	s_add_u32 s8, s8, 0xc000
	s_addc_u32 s9, s9, 0
	ds_read_b128 v[2:5], v93 offset:96
	ds_read_b128 v[6:9], v93 offset:4192
	ds_read_b128 v[10:13], v93 offset:8288
	ds_read_b128 v[14:17], v93 offset:12384
	ds_read_b128 v[18:21], v93 offset:16480
	ds_read_b128 v[22:25], v93 offset:20576
	ds_read_b128 v[26:29], v93 offset:24672
	ds_read_b128 v[30:33], v93 offset:28768
	ds_read_b128 v[34:37], v93 offset:32864
	ds_read_b128 v[38:41], v93 offset:36960
	ds_read_b128 v[42:45], v93 offset:41056
	ds_read_b128 v[126:129], v93 offset:45152
	ds_read_b128 v[130:133], v93 offset:49248
	ds_read_b128 v[134:137], v93 offset:53344
	ds_read_b128 v[138:141], v93 offset:57440
	ds_read_b128 v[142:145], v93 offset:61536
	s_waitcnt vmcnt(28)
	s_waitcnt lgkmcnt(8)
	v_pk_fma_f32 v[146:147], v[2:3], v[118:119], v[146:147]
	v_pk_fma_f32 v[148:149], v[6:7], v[118:119], v[148:149]
	v_pk_fma_f32 v[150:151], v[10:11], v[118:119], v[150:151]
	v_pk_fma_f32 v[152:153], v[14:15], v[118:119], v[152:153]
	v_pk_fma_f32 v[154:155], v[18:19], v[118:119], v[154:155]
	v_pk_fma_f32 v[156:157], v[22:23], v[118:119], v[156:157]
	v_pk_fma_f32 v[158:159], v[26:27], v[118:119], v[158:159]
	v_pk_fma_f32 v[168:169], v[30:31], v[118:119], v[168:169]
	v_pk_fma_f32 v[146:147], v[4:5], v[120:121], v[146:147]
	v_pk_fma_f32 v[148:149], v[8:9], v[120:121], v[148:149]
	v_pk_fma_f32 v[150:151], v[12:13], v[120:121], v[150:151]
	v_pk_fma_f32 v[152:153], v[16:17], v[120:121], v[152:153]
	v_pk_fma_f32 v[154:155], v[20:21], v[120:121], v[154:155]
	v_pk_fma_f32 v[156:157], v[24:25], v[120:121], v[156:157]
	v_pk_fma_f32 v[158:159], v[28:29], v[120:121], v[158:159]
	v_pk_fma_f32 v[168:169], v[32:33], v[120:121], v[168:169]
	s_waitcnt lgkmcnt(0)
; __device__ NOINL void prep_mod(const float* c, const float* wada, const float* bada, float* mod, LAS unsigned char* lds, int wv) {
;     ...
;             for (int kk = 0; kk < 256; ++kk) { const float w = wp[(size_t)kk * 12288];
; #pragma unroll
;                 for (int b = 0; b < 16; ++b) acc[b] += cs[b * 1024 + kq * 256 + kk] * w; }
	v_pk_fma_f32 v[170:171], v[34:35], v[118:119], v[170:171]
	v_pk_fma_f32 v[172:173], v[38:39], v[118:119], v[172:173]
	v_pk_fma_f32 v[174:175], v[42:43], v[118:119], v[174:175]
	v_pk_fma_f32 v[176:177], v[126:127], v[118:119], v[176:177]
	v_pk_fma_f32 v[178:179], v[130:131], v[118:119], v[178:179]
	v_pk_fma_f32 v[180:181], v[134:135], v[118:119], v[180:181]
	v_pk_fma_f32 v[182:183], v[138:139], v[118:119], v[182:183]
	v_pk_fma_f32 v[184:185], v[142:143], v[118:119], v[184:185]
	v_pk_fma_f32 v[170:171], v[36:37], v[120:121], v[170:171]
	v_pk_fma_f32 v[172:173], v[40:41], v[120:121], v[172:173]
	v_pk_fma_f32 v[174:175], v[44:45], v[120:121], v[174:175]
	v_pk_fma_f32 v[176:177], v[128:129], v[120:121], v[176:177]
	v_pk_fma_f32 v[178:179], v[132:133], v[120:121], v[178:179]
	v_pk_fma_f32 v[180:181], v[136:137], v[120:121], v[180:181]
	v_pk_fma_f32 v[182:183], v[140:141], v[120:121], v[182:183]
	v_pk_fma_f32 v[184:185], v[144:145], v[120:121], v[184:185]
	global_load_dword v118, v186, s[8:9]
	s_add_u32 s8, s8, 0xc000
	s_addc_u32 s9, s9, 0
	global_load_dword v119, v186, s[8:9]
	s_add_u32 s8, s8, 0xc000
	s_addc_u32 s9, s9, 0
	global_load_dword v120, v186, s[8:9]
	s_add_u32 s8, s8, 0xc000
	s_addc_u32 s9, s9, 0
	global_load_dword v121, v186, s[8:9]
	s_add_u32 s8, s8, 0xc000
	s_addc_u32 s9, s9, 0
	ds_read_b128 v[2:5], v93 offset:112
	ds_read_b128 v[6:9], v93 offset:4208
	ds_read_b128 v[10:13], v93 offset:8304
	ds_read_b128 v[14:17], v93 offset:12400
	ds_read_b128 v[18:21], v93 offset:16496
	ds_read_b128 v[22:25], v93 offset:20592
	ds_read_b128 v[26:29], v93 offset:24688
	ds_read_b128 v[30:33], v93 offset:28784
	ds_read_b128 v[34:37], v93 offset:32880
	ds_read_b128 v[38:41], v93 offset:36976
	ds_read_b128 v[42:45], v93 offset:41072
	ds_read_b128 v[126:129], v93 offset:45168
	ds_read_b128 v[130:133], v93 offset:49264
	ds_read_b128 v[134:137], v93 offset:53360
	ds_read_b128 v[138:141], v93 offset:57456
	ds_read_b128 v[142:145], v93 offset:61552
	s_waitcnt vmcnt(28)
	s_waitcnt lgkmcnt(8)
	v_pk_fma_f32 v[146:147], v[2:3], v[122:123], v[146:147]
	v_pk_fma_f32 v[148:149], v[6:7], v[122:123], v[148:149]
	v_pk_fma_f32 v[150:151], v[10:11], v[122:123], v[150:151]
	v_pk_fma_f32 v[152:153], v[14:15], v[122:123], v[152:153]
	v_pk_fma_f32 v[154:155], v[18:19], v[122:123], v[154:155]
	v_pk_fma_f32 v[156:157], v[22:23], v[122:123], v[156:157]
	v_pk_fma_f32 v[158:159], v[26:27], v[122:123], v[158:159]
	v_pk_fma_f32 v[168:169], v[30:31], v[122:123], v[168:169]
	v_pk_fma_f32 v[146:147], v[4:5], v[124:125], v[146:147]
	v_pk_fma_f32 v[148:149], v[8:9], v[124:125], v[148:149]
	v_pk_fma_f32 v[150:151], v[12:13], v[124:125], v[150:151]
	v_pk_fma_f32 v[152:153], v[16:17], v[124:125], v[152:153]
	v_pk_fma_f32 v[154:155], v[20:21], v[124:125], v[154:155]
	v_pk_fma_f32 v[156:157], v[24:25], v[124:125], v[156:157]
	v_pk_fma_f32 v[158:159], v[28:29], v[124:125], v[158:159]
	v_pk_fma_f32 v[168:169], v[32:33], v[124:125], v[168:169]
	s_waitcnt lgkmcnt(0)
	v_pk_fma_f32 v[170:171], v[34:35], v[122:123], v[170:171]
	v_pk_fma_f32 v[172:173], v[38:39], v[122:123], v[172:173]
	v_pk_fma_f32 v[174:175], v[42:43], v[122:123], v[174:175]
	v_pk_fma_f32 v[176:177], v[126:127], v[122:123], v[176:177]
	v_pk_fma_f32 v[178:179], v[130:131], v[122:123], v[178:179]
	v_pk_fma_f32 v[180:181], v[134:135], v[122:123], v[180:181]
	v_pk_fma_f32 v[182:183], v[138:139], v[122:123], v[182:183]
	v_pk_fma_f32 v[184:185], v[142:143], v[122:123], v[184:185]
	v_pk_fma_f32 v[170:171], v[36:37], v[124:125], v[170:171]
	v_pk_fma_f32 v[172:173], v[40:41], v[124:125], v[172:173]
	v_pk_fma_f32 v[174:175], v[44:45], v[124:125], v[174:175]
	v_pk_fma_f32 v[176:177], v[128:129], v[124:125], v[176:177]
	v_pk_fma_f32 v[178:179], v[132:133], v[124:125], v[178:179]
	v_pk_fma_f32 v[180:181], v[136:137], v[124:125], v[180:181]
	v_pk_fma_f32 v[182:183], v[140:141], v[124:125], v[182:183]
	v_pk_fma_f32 v[184:185], v[144:145], v[124:125], v[184:185]
	v_add_u32_e32 v93, 0x80, v93
	s_add_i32 s24, s24, 1
	s_cmp_eq_u32 s24, 16
	s_cbranch_scc0 .Lpm_loop
; __device__ NOINL void prep_mod(const float* c, const float* wada, const float* bada, float* mod, LAS unsigned char* lds, int wv) {
;     ...
;         }
;         __syncthreads();
; #pragma unroll
;         for (int b = 0; b < 16; ++b) red[(kq * 16 + b) * 128 + j] = acc[b];
;         __syncthreads();
;         for (int i = 0; i < 4; ++i) { const int o = i * 512 + tid, b = o >> 7, jj = o & 127;
;             const float s = red[(0 * 16 + b) * 128 + jj] + red[(1 * 16 + b) * 128 + jj] + red[(2 * 16 + b) * 128 + jj] + red[(3 * 16 + b) * 128 + jj] + bada[l * 12288 + j0 + jj];
;             mod[((size_t)l * 16 + b) * 12288 + j0 + jj] = s; }
	s_waitcnt vmcnt(0)
	v_add_f32_e32 v70, v146, v147
	v_add_f32_e32 v71, v148, v149
	v_add_f32_e32 v76, v150, v151
	v_add_f32_e32 v77, v152, v153
	v_add_f32_e32 v74, v154, v155
	v_add_f32_e32 v75, v156, v157
	v_add_f32_e32 v72, v158, v159
	v_add_f32_e32 v73, v168, v169
	v_add_f32_e32 v68, v170, v171
	v_add_f32_e32 v69, v172, v173
	v_add_f32_e32 v66, v174, v175
	v_add_f32_e32 v67, v176, v177
	v_add_f32_e32 v64, v178, v179
	v_add_f32_e32 v65, v180, v181
	v_add_f32_e32 v62, v182, v183
	v_add_f32_e32 v63, v184, v185
	s_mul_i32 s8, s2, 0x3000
	s_add_i32 s8, s8, s6
	v_or_b32_e32 v2, s8, v78
	v_ashrrev_i32_e32 v3, 31, v2
	v_lshl_add_u64 v[2:3], v[2:3], 2, s[58:59]
	s_barrier
	ds_write2st64_b32 v92, v70, v71 offset1:2
	ds_write2st64_b32 v92, v76, v77 offset0:4 offset1:6
	ds_write2st64_b32 v92, v74, v75 offset0:8 offset1:10
	ds_write2st64_b32 v92, v72, v73 offset0:12 offset1:14
	ds_write2st64_b32 v92, v68, v69 offset0:16 offset1:18
	ds_write2st64_b32 v92, v66, v67 offset0:20 offset1:22
	ds_write2st64_b32 v92, v64, v65 offset0:24 offset1:26
	ds_write2st64_b32 v92, v62, v63 offset0:28 offset1:30
	s_waitcnt lgkmcnt(0)
	s_barrier
	flat_load_dword v12, v[2:3]
	ds_read2st64_b32 v[6:7], v82 offset0:32 offset1:64
	ds_read_b32 v13, v81
	ds_read_b32 v14, v82 offset:24576
	s_lshl_b64 s[2:3], s[2:3], 4
	v_lshl_add_u64 v[4:5], s[6:7], 2, v[52:53]
	v_lshl_add_u64 v[8:9], s[2:3], 0, v[46:47]
	s_waitcnt lgkmcnt(0)
	v_add_f32_e32 v6, v13, v6
	v_add_f32_e32 v6, v6, v7
	v_mad_u64_u32 v[10:11], s[6:7], v8, s15, v[4:5]
	v_add_f32_e32 v6, v6, v14
	v_mad_i32_i24 v11, v9, s15, v11
	s_waitcnt vmcnt(0)
	v_add_f32_e32 v6, v6, v12
	flat_store_dword v[10:11], v6
	flat_load_dword v12, v[2:3]
	ds_read2st64_b32 v[8:9], v84 offset0:32 offset1:64
	ds_read_b32 v13, v83
	ds_read_b32 v14, v84 offset:24576
	v_lshl_add_u64 v[6:7], s[2:3], 0, v[54:55]
	v_mad_u64_u32 v[10:11], s[6:7], v6, s15, v[4:5]
	s_waitcnt lgkmcnt(0)
	v_add_f32_e32 v6, v13, v8
	v_add_f32_e32 v6, v6, v9
	v_add_f32_e32 v6, v6, v14
	v_mad_i32_i24 v11, v7, s15, v11
	s_waitcnt vmcnt(0)
	v_add_f32_e32 v6, v6, v12
	flat_store_dword v[10:11], v6
	flat_load_dword v12, v[2:3]
	ds_read2st64_b32 v[8:9], v86 offset0:32 offset1:64
	ds_read_b32 v13, v85
	ds_read_b32 v14, v86 offset:24576
	v_lshl_add_u64 v[6:7], s[2:3], 0, v[56:57]
	v_mad_u64_u32 v[10:11], s[6:7], v6, s15, v[4:5]
	s_waitcnt lgkmcnt(0)
	v_add_f32_e32 v6, v13, v8
	v_add_f32_e32 v6, v6, v9
	v_add_f32_e32 v6, v6, v14
	v_mad_i32_i24 v11, v7, s15, v11
	s_waitcnt vmcnt(0)
	v_add_f32_e32 v6, v6, v12
	flat_store_dword v[10:11], v6
	flat_load_dword v8, v[2:3]
	s_load_dword s6, s[0:1], 0xa0
	ds_read2st64_b32 v[6:7], v88 offset0:32 offset1:64
	ds_read_b32 v9, v87
	ds_read_b32 v10, v88 offset:24576
	v_lshl_add_u64 v[2:3], s[2:3], 0, v[58:59]
	v_mad_u64_u32 v[4:5], s[2:3], v2, s15, v[4:5]
	s_waitcnt lgkmcnt(0)
	v_add_f32_e32 v2, v9, v6
	v_add_f32_e32 v2, v2, v7
	v_add_f32_e32 v2, v2, v10
	v_mad_i32_i24 v5, v3, s15, v5
	s_waitcnt vmcnt(0)
	v_add_f32_e32 v2, v2, v8
	flat_store_dword v[4:5], v2
	s_add_i32 s10, s6, s10
	s_cmpk_gt_i32 s10, 0xbf
	s_cbranch_scc0 .LBB0_2

; __device__ __forceinline__ int obx() { int b = blockIdx.x; asm volatile("" : "+s"(b)); return b; }
; __device__ __forceinline__ int ogx() { int g = gridDim.x; asm volatile("" : "+s"(g)); return g; }
; template <bool DO_LN, bool DO_H, bool DO_GATES, bool WRITE_X> ...
;     ...
;         __syncthreads();
; #pragma unroll 4
;         for (int i = 0; i < 32; ++i) { const int idx = i * 512 + tid, k = idx >> 3, gg = idx & 7; wif[gg * 2048 + k] = wi[(size_t)k * DIN + gg]; }
;         __syncthreads();
;     }
;     for (int grp = obx() * 8 + wave; grp < NTOK / 16; grp += ogx() * 8) {
;         const int row0 = grp * 16;
;         const float* mb = modl + (size_t)(row0 >> 11) * 12288 + lane * 4;
.LBB0_167:
	v_ashrrev_i32_e32 v7, 3, v2
	v_mad_i64_i32 v[4:5], s[12:13], v7, s11, v[0:1]
	v_lshl_add_u32 v6, v7, 2, v3
	s_mov_b32 s10, 0x380800
	s_mov_b32 s11, 0
	global_load_dword v100, v[4:5], off
	v_lshl_add_u64 v[4:5], v[4:5], 0, s[10:11]
	global_load_dword v101, v[4:5], off
	v_lshl_add_u64 v[4:5], v[4:5], 0, s[10:11]
	global_load_dword v102, v[4:5], off
	v_lshl_add_u64 v[4:5], v[4:5], 0, s[10:11]
	global_load_dword v103, v[4:5], off
	v_lshl_add_u64 v[4:5], v[4:5], 0, s[10:11]
	global_load_dword v104, v[4:5], off
	v_lshl_add_u64 v[4:5], v[4:5], 0, s[10:11]
	global_load_dword v105, v[4:5], off
	v_lshl_add_u64 v[4:5], v[4:5], 0, s[10:11]
	global_load_dword v106, v[4:5], off
	v_lshl_add_u64 v[4:5], v[4:5], 0, s[10:11]
	global_load_dword v107, v[4:5], off
	v_lshl_add_u64 v[4:5], v[4:5], 0, s[10:11]
	global_load_dword v108, v[4:5], off
	v_lshl_add_u64 v[4:5], v[4:5], 0, s[10:11]
	global_load_dword v109, v[4:5], off
	v_lshl_add_u64 v[4:5], v[4:5], 0, s[10:11]
	global_load_dword v110, v[4:5], off
	v_lshl_add_u64 v[4:5], v[4:5], 0, s[10:11]
	global_load_dword v111, v[4:5], off
	v_lshl_add_u64 v[4:5], v[4:5], 0, s[10:11]
	global_load_dword v112, v[4:5], off
	v_lshl_add_u64 v[4:5], v[4:5], 0, s[10:11]
	global_load_dword v113, v[4:5], off
	v_lshl_add_u64 v[4:5], v[4:5], 0, s[10:11]
	global_load_dword v114, v[4:5], off
	v_lshl_add_u64 v[4:5], v[4:5], 0, s[10:11]
	global_load_dword v115, v[4:5], off
	v_lshl_add_u64 v[4:5], v[4:5], 0, s[10:11]
	global_load_dword v116, v[4:5], off
	v_lshl_add_u64 v[4:5], v[4:5], 0, s[10:11]
	global_load_dword v117, v[4:5], off
	v_lshl_add_u64 v[4:5], v[4:5], 0, s[10:11]
	global_load_dword v118, v[4:5], off
	v_lshl_add_u64 v[4:5], v[4:5], 0, s[10:11]
	global_load_dword v119, v[4:5], off
	v_lshl_add_u64 v[4:5], v[4:5], 0, s[10:11]
	global_load_dword v120, v[4:5], off
	v_lshl_add_u64 v[4:5], v[4:5], 0, s[10:11]
	global_load_dword v121, v[4:5], off
	v_lshl_add_u64 v[4:5], v[4:5], 0, s[10:11]
	global_load_dword v122, v[4:5], off
	v_lshl_add_u64 v[4:5], v[4:5], 0, s[10:11]
	global_load_dword v123, v[4:5], off
	v_lshl_add_u64 v[4:5], v[4:5], 0, s[10:11]
	global_load_dword v124, v[4:5], off
	v_lshl_add_u64 v[4:5], v[4:5], 0, s[10:11]
	global_load_dword v125, v[4:5], off
	v_lshl_add_u64 v[4:5], v[4:5], 0, s[10:11]
	global_load_dword v126, v[4:5], off
	v_lshl_add_u64 v[4:5], v[4:5], 0, s[10:11]
	global_load_dword v127, v[4:5], off
	v_lshl_add_u64 v[4:5], v[4:5], 0, s[10:11]
	global_load_dword v128, v[4:5], off
	v_lshl_add_u64 v[4:5], v[4:5], 0, s[10:11]
	global_load_dword v129, v[4:5], off
	v_lshl_add_u64 v[4:5], v[4:5], 0, s[10:11]
	global_load_dword v130, v[4:5], off
	v_lshl_add_u64 v[4:5], v[4:5], 0, s[10:11]
	global_load_dword v131, v[4:5], off
	v_lshl_add_u64 v[4:5], v[4:5], 0, s[10:11]
	s_waitcnt vmcnt(31)
	ds_write_b32 v6, v100
	s_waitcnt vmcnt(30)
	ds_write_b32 v6, v101 offset:256
	s_waitcnt vmcnt(29)
	ds_write_b32 v6, v102 offset:512
	s_waitcnt vmcnt(28)
	ds_write_b32 v6, v103 offset:768
	s_waitcnt vmcnt(27)
	ds_write_b32 v6, v104 offset:1024
	s_waitcnt vmcnt(26)
	ds_write_b32 v6, v105 offset:1280
	s_waitcnt vmcnt(25)
	ds_write_b32 v6, v106 offset:1536
	s_waitcnt vmcnt(24)
	ds_write_b32 v6, v107 offset:1792
	s_waitcnt vmcnt(23)
	ds_write_b32 v6, v108 offset:2048
	s_waitcnt vmcnt(22)
	ds_write_b32 v6, v109 offset:2304
	s_waitcnt vmcnt(21)
	ds_write_b32 v6, v110 offset:2560
	s_waitcnt vmcnt(20)
	ds_write_b32 v6, v111 offset:2816
	s_waitcnt vmcnt(19)
	ds_write_b32 v6, v112 offset:3072
	s_waitcnt vmcnt(18)
	ds_write_b32 v6, v113 offset:3328
	s_waitcnt vmcnt(17)
	ds_write_b32 v6, v114 offset:3584
	s_waitcnt vmcnt(16)
	ds_write_b32 v6, v115 offset:3840
	s_waitcnt vmcnt(15)
	ds_write_b32 v6, v116 offset:4096
	s_waitcnt vmcnt(14)
	ds_write_b32 v6, v117 offset:4352
	s_waitcnt vmcnt(13)
	ds_write_b32 v6, v118 offset:4608
	s_waitcnt vmcnt(12)
	ds_write_b32 v6, v119 offset:4864
	s_waitcnt vmcnt(11)
	ds_write_b32 v6, v120 offset:5120
	s_waitcnt vmcnt(10)
	ds_write_b32 v6, v121 offset:5376
	s_waitcnt vmcnt(9)
	ds_write_b32 v6, v122 offset:5632
	s_waitcnt vmcnt(8)
	ds_write_b32 v6, v123 offset:5888
	s_waitcnt vmcnt(7)
	ds_write_b32 v6, v124 offset:6144
	s_waitcnt vmcnt(6)
	ds_write_b32 v6, v125 offset:6400
	s_waitcnt vmcnt(5)
	ds_write_b32 v6, v126 offset:6656
	s_waitcnt vmcnt(4)
	ds_write_b32 v6, v127 offset:6912
	s_waitcnt vmcnt(3)
	ds_write_b32 v6, v128 offset:7168
	s_waitcnt vmcnt(2)
	ds_write_b32 v6, v129 offset:7424
	s_waitcnt vmcnt(1)
	ds_write_b32 v6, v130 offset:7680
	s_waitcnt vmcnt(0)
	ds_write_b32 v6, v131 offset:7936
	s_mov_b32 s10, s31
	v_ashrrev_i32_e32 v0, 6, v2
	s_waitcnt lgkmcnt(0)
	s_barrier
	s_nop 0
	v_lshl_add_u32 v69, s10, 3, v0
	s_movk_i32 s10, 0x800
	v_cmp_gt_i32_e32 vcc, s10, v69
	s_and_saveexec_b64 s[10:11], vcc
	s_cbranch_execz .LBB0_177
	v_and_b32_e32 v2, 63, v2
	v_lshlrev_b32_e32 v3, 2, v2
	v_lshlrev_b32_e32 v0, 4, v2
	v_mov_b32_e32 v1, 0
	v_lshl_add_u64 v[64:65], s[2:3], 0, v[0:1]
	v_lshl_add_u64 v[66:67], s[0:1], 0, v[0:1]
	v_add_u32_e32 v138, 0, v0
	v_xor_b32_e32 v139, 0x80, v3
	v_xor_b32_e32 v140, 64, v3
	v_xor_b32_e32 v141, 32, v3
	v_xor_b32_e32 v142, 16, v3
	v_xor_b32_e32 v143, 8, v3
	v_xor_b32_e32 v144, 4, v3
	v_cmp_eq_u32_e64 s[0:1], 0, v2
	v_lshlrev_b32_e32 v68, 3, v2
	s_mov_b64 s[12:13], 0
	s_mov_b32 s16, 0xc000
	s_movk_i32 s17, 0x3000
	s_movk_i32 s18, 0x1000
	s_mov_b32 s19, 0x8e00000
	s_mov_b64 s[14:15], 0x1000
	s_movk_i32 s20, 0x7ff
	s_branch .LBB0_171

; __device__ __forceinline__ int obx() { int b = blockIdx.x; asm volatile("" : "+s"(b)); return b; }
; __device__ __forceinline__ int ogx() { int g = gridDim.x; asm volatile("" : "+s"(g)); return g; }
; template <bool DO_LN, bool DO_H, bool DO_GATES, bool WRITE_X> ...
;     ...
;         __syncthreads();
; #pragma unroll 4
;         for (int i = 0; i < 32; ++i) { const int idx = i * 512 + tid, k = idx >> 3, gg = idx & 7; wif[gg * 2048 + k] = wi[(size_t)k * DIN + gg]; }
;         __syncthreads();
;     }
;     for (int grp = obx() * 8 + wave; grp < NTOK / 16; grp += ogx() * 8) {
;         const int row0 = grp * 16;
;         const float* mb = modl + (size_t)(row0 >> 11) * 12288 + lane * 4;
.LBB0_730:
	v_ashrrev_i32_e32 v8, 3, v4
	v_mad_i64_i32 v[6:7], s[16:17], v8, s41, v[2:3]
	v_lshl_add_u32 v5, v8, 2, v1
	s_mov_b32 s10, 0x380800
	s_mov_b32 s11, 0
	global_load_dword v100, v[6:7], off
	v_lshl_add_u64 v[6:7], v[6:7], 0, s[10:11]
	global_load_dword v101, v[6:7], off
	v_lshl_add_u64 v[6:7], v[6:7], 0, s[10:11]
	global_load_dword v102, v[6:7], off
	v_lshl_add_u64 v[6:7], v[6:7], 0, s[10:11]
	global_load_dword v103, v[6:7], off
	v_lshl_add_u64 v[6:7], v[6:7], 0, s[10:11]
	global_load_dword v104, v[6:7], off
	v_lshl_add_u64 v[6:7], v[6:7], 0, s[10:11]
	global_load_dword v105, v[6:7], off
	v_lshl_add_u64 v[6:7], v[6:7], 0, s[10:11]
	global_load_dword v106, v[6:7], off
	v_lshl_add_u64 v[6:7], v[6:7], 0, s[10:11]
	global_load_dword v107, v[6:7], off
	v_lshl_add_u64 v[6:7], v[6:7], 0, s[10:11]
	global_load_dword v108, v[6:7], off
	v_lshl_add_u64 v[6:7], v[6:7], 0, s[10:11]
	global_load_dword v109, v[6:7], off
	v_lshl_add_u64 v[6:7], v[6:7], 0, s[10:11]
	global_load_dword v110, v[6:7], off
	v_lshl_add_u64 v[6:7], v[6:7], 0, s[10:11]
	global_load_dword v111, v[6:7], off
	v_lshl_add_u64 v[6:7], v[6:7], 0, s[10:11]
	global_load_dword v112, v[6:7], off
	v_lshl_add_u64 v[6:7], v[6:7], 0, s[10:11]
	global_load_dword v113, v[6:7], off
	v_lshl_add_u64 v[6:7], v[6:7], 0, s[10:11]
	global_load_dword v114, v[6:7], off
	v_lshl_add_u64 v[6:7], v[6:7], 0, s[10:11]
	global_load_dword v115, v[6:7], off
	v_lshl_add_u64 v[6:7], v[6:7], 0, s[10:11]
	global_load_dword v116, v[6:7], off
	v_lshl_add_u64 v[6:7], v[6:7], 0, s[10:11]
	global_load_dword v117, v[6:7], off
	v_lshl_add_u64 v[6:7], v[6:7], 0, s[10:11]
	global_load_dword v118, v[6:7], off
	v_lshl_add_u64 v[6:7], v[6:7], 0, s[10:11]
	global_load_dword v119, v[6:7], off
	v_lshl_add_u64 v[6:7], v[6:7], 0, s[10:11]
	global_load_dword v120, v[6:7], off
	v_lshl_add_u64 v[6:7], v[6:7], 0, s[10:11]
	global_load_dword v121, v[6:7], off
	v_lshl_add_u64 v[6:7], v[6:7], 0, s[10:11]
	global_load_dword v122, v[6:7], off
	v_lshl_add_u64 v[6:7], v[6:7], 0, s[10:11]
	global_load_dword v123, v[6:7], off
	v_lshl_add_u64 v[6:7], v[6:7], 0, s[10:11]
	global_load_dword v124, v[6:7], off
	v_lshl_add_u64 v[6:7], v[6:7], 0, s[10:11]
	global_load_dword v125, v[6:7], off
	v_lshl_add_u64 v[6:7], v[6:7], 0, s[10:11]
	global_load_dword v126, v[6:7], off
	v_lshl_add_u64 v[6:7], v[6:7], 0, s[10:11]
	global_load_dword v127, v[6:7], off
	v_lshl_add_u64 v[6:7], v[6:7], 0, s[10:11]
	global_load_dword v128, v[6:7], off
	v_lshl_add_u64 v[6:7], v[6:7], 0, s[10:11]
	global_load_dword v129, v[6:7], off
	v_lshl_add_u64 v[6:7], v[6:7], 0, s[10:11]
	global_load_dword v130, v[6:7], off
	v_lshl_add_u64 v[6:7], v[6:7], 0, s[10:11]
	global_load_dword v131, v[6:7], off
	v_lshl_add_u64 v[6:7], v[6:7], 0, s[10:11]
	s_waitcnt vmcnt(31)
	ds_write_b32 v5, v100
	s_waitcnt vmcnt(30)
	ds_write_b32 v5, v101 offset:256
	s_waitcnt vmcnt(29)
	ds_write_b32 v5, v102 offset:512
	s_waitcnt vmcnt(28)
	ds_write_b32 v5, v103 offset:768
	s_waitcnt vmcnt(27)
	ds_write_b32 v5, v104 offset:1024
	s_waitcnt vmcnt(26)
	ds_write_b32 v5, v105 offset:1280
	s_waitcnt vmcnt(25)
	ds_write_b32 v5, v106 offset:1536
	s_waitcnt vmcnt(24)
	ds_write_b32 v5, v107 offset:1792
	s_waitcnt vmcnt(23)
	ds_write_b32 v5, v108 offset:2048
	s_waitcnt vmcnt(22)
	ds_write_b32 v5, v109 offset:2304
	s_waitcnt vmcnt(21)
	ds_write_b32 v5, v110 offset:2560
	s_waitcnt vmcnt(20)
	ds_write_b32 v5, v111 offset:2816
	s_waitcnt vmcnt(19)
	ds_write_b32 v5, v112 offset:3072
	s_waitcnt vmcnt(18)
	ds_write_b32 v5, v113 offset:3328
	s_waitcnt vmcnt(17)
	ds_write_b32 v5, v114 offset:3584
	s_waitcnt vmcnt(16)
	ds_write_b32 v5, v115 offset:3840
	s_waitcnt vmcnt(15)
	ds_write_b32 v5, v116 offset:4096
	s_waitcnt vmcnt(14)
	ds_write_b32 v5, v117 offset:4352
	s_waitcnt vmcnt(13)
	ds_write_b32 v5, v118 offset:4608
	s_waitcnt vmcnt(12)
	ds_write_b32 v5, v119 offset:4864
	s_waitcnt vmcnt(11)
	ds_write_b32 v5, v120 offset:5120
	s_waitcnt vmcnt(10)
	ds_write_b32 v5, v121 offset:5376
	s_waitcnt vmcnt(9)
	ds_write_b32 v5, v122 offset:5632
	s_waitcnt vmcnt(8)
	ds_write_b32 v5, v123 offset:5888
	s_waitcnt vmcnt(7)
	ds_write_b32 v5, v124 offset:6144
	s_waitcnt vmcnt(6)
	ds_write_b32 v5, v125 offset:6400
	s_waitcnt vmcnt(5)
	ds_write_b32 v5, v126 offset:6656
	s_waitcnt vmcnt(4)
	ds_write_b32 v5, v127 offset:6912
	s_waitcnt vmcnt(3)
	ds_write_b32 v5, v128 offset:7168
	s_waitcnt vmcnt(2)
	ds_write_b32 v5, v129 offset:7424
	s_waitcnt vmcnt(1)
	ds_write_b32 v5, v130 offset:7680
	s_waitcnt vmcnt(0)
	ds_write_b32 v5, v131 offset:7936
	s_mov_b32 s10, s31
	v_ashrrev_i32_e32 v1, 6, v4
	s_waitcnt lgkmcnt(0)
	s_barrier
	s_nop 0
	v_lshl_add_u32 v1, s10, 3, v1
	s_movk_i32 s10, 0x800
	v_cmp_gt_i32_e32 vcc, s10, v1
	s_and_saveexec_b64 s[10:11], vcc
	s_cbranch_execz .LBB0_742
	v_and_b32_e32 v4, 63, v4
	v_lshlrev_b32_e32 v2, 4, v4
	v_mov_b32_e32 v3, v0
	v_lshl_add_u64 v[68:69], s[12:13], 0, v[2:3]
	v_lshl_add_u64 v[70:71], s[14:15], 0, v[2:3]
	v_lshl_add_u64 v[72:73], s[2:3], 0, v[2:3]
	s_mov_b64 s[2:3], 0x1400
	v_lshl_add_u64 v[78:79], v[68:69], 0, s[2:3]
	v_lshl_add_u64 v[80:81], v[70:71], 0, s[2:3]
	s_mov_b64 s[2:3], 0x1800
	v_lshlrev_b32_e32 v5, 2, v4
	v_lshl_add_u64 v[82:83], v[68:69], 0, s[2:3]
	v_lshl_add_u64 v[84:85], v[70:71], 0, s[2:3]
	s_mov_b64 s[2:3], 0x1c00
	v_lshl_add_u64 v[66:67], s[0:1], 0, v[2:3]
	v_xor_b32_e32 v91, 0x80, v5
	v_xor_b32_e32 v167, 64, v5
	v_xor_b32_e32 v168, 32, v5
	v_xor_b32_e32 v169, 16, v5
	v_xor_b32_e32 v170, 8, v5
	v_xor_b32_e32 v171, 4, v5
	v_cmp_eq_u32_e64 s[0:1], 0, v4
	v_add_u32_e32 v172, 0, v2
	v_lshl_add_u64 v[74:75], v[68:69], 0, s[94:95]
	v_lshl_add_u64 v[76:77], v[70:71], 0, s[94:95]
	v_lshl_add_u64 v[86:87], v[68:69], 0, s[2:3]
	v_lshl_add_u64 v[88:89], v[70:71], 0, s[2:3]
	v_lshlrev_b32_e32 v90, 3, v4
	s_mov_b64 s[12:13], 0
	s_branch .LBB0_734
